# v21 with all priority changes removed from the 10 looped GEMM mainloops (priority-free mainloop)
# speedup vs baseline: 1.0085x; 1.0085x over previous
; #define PG8_STAGE(bufoff, gbase, voff) do { _Pragma("unroll") for (int _i = 0; _i < 2; ++_i) \
;         __builtin_amdgcn_global_load_lds((const unsigned*)((const char*)(gbase) + (voff)[_i]), (LAS unsigned*)(lds + (bufoff) + ldsw + _i * 8192), 16, 0, 0); } while (0)
; #define PG8_LDA(dst, b, h) do { _Pragma("unroll") for (int m = 0; m < 4; ++m) _Pragma("unroll") for (int k = 0; k < 2; ++k) dst[m][k] = *(const LAS bf16x8*)(lds + PG8_SA(b, h) + aoff + m * 2048 + k * 1024); } while (0)
; #define PG8_LDB(dst, b, h) do { _Pragma("unroll") for (int n = 0; n < 2; ++n) _Pragma("unroll") for (int k = 0; k < 2; ++k) dst[n][k] = *(const LAS bf16x8*)(lds + PG8_SB(b, h) + boff + n * 2048 + k * 1024); } while (0)
; #define PG8_MMA(ai, bj, At, Bt) do { __builtin_amdgcn_s_setprio(1); _Pragma("unroll") for (int m = 0; m < 4; ++m) _Pragma("unroll") for (int n = 0; n < 2; ++n) _Pragma("unroll") for (int k = 0; k < 2; ++k) \
;         acc[ai][bj][m][n] = __builtin_amdgcn_mfma_f32_16x16x32_bf16(Bt[n][k], At[m][k], acc[ai][bj][m][n], 0, 0, 0); __builtin_amdgcn_s_setprio(0); } while (0)
; #define PG8_WAIT_V(n) asm volatile("s_waitcnt vmcnt(" #n ")" ::: "memory")
; #define PG8_WAIT_L(n) asm volatile("s_waitcnt lgkmcnt(" #n ")" ::: "memory")
; template <class Epi, class Sched>
; __device__ __forceinline__ void gemm_phase(LAS unsigned char* lds, const GemmP g, const Sched& S, const Epi& E, int tid) {
;     ...
;         for (int t = 0; t < nt; t += 2) {
;             const bool last = (t == nt - 2);
;             const char* a1 = cA + (size_t)(t + 1) * kstep;
;             const char* a2 = last ? nA : cA + (size_t)(t + 2) * kstep; const char* b2 = last ? nB : cB + (size_t)(t + 2) * kstep;
;             const char* a3 = a2 + kstep; const char* b3 = b2 + kstep;
;             PG8_LDB(B0, 0, 0); PG8_LDB(B1, 0, 1); PG8_SCHED; PG8_LDA(At, 0, 0); PG8_STAGE(PG8_SA(1, 1), a1 + hstepA, voffA);
;             PG8_WAIT_V(8); PG8_WAIT_L(0); PG8_BAR; PG8_MMA(0, 0, At, B0); PG8_MMA(0, 1, At, B1); PG8_BAR; PG8_SCHED;
;     ...
; #pragma unroll
;         for (int a = 0; a < 2; ++a)
; #pragma unroll
;             for (int b = 0; b < 2; ++b)
; #pragma unroll
;                 for (int m = 0; m < 4; ++m)
; #pragma unroll
;                     for (int n = 0; n < 2; ++n) acc[a][b][m][n] = (f32x4){0.f, 0.f, 0.f, 0.f};
;         cur = nxt; cA = nA; cB = nB; ++ui;
;         if (wr == 1) PG8_BAR;
.LBB0_222:
	s_add_u32 s69, s40, 0x100
	s_addc_u32 s70, s41, 0
	s_add_u32 s38, s38, 0x40080
	v_mov_b32_e32 v0, 0
	s_addc_u32 s39, s39, 0
	s_mov_b32 s71, -2
	v_mov_b32_e32 v1, v0
	v_mov_b32_e32 v2, v0
	v_mov_b32_e32 v3, v0
	v_mov_b32_e32 v4, v0
	v_mov_b32_e32 v5, v0
	v_mov_b32_e32 v6, v0
	v_mov_b32_e32 v7, v0
	v_mov_b32_e32 v8, v0
	v_mov_b32_e32 v9, v0
	v_mov_b32_e32 v10, v0
	v_mov_b32_e32 v11, v0
	v_mov_b32_e32 v12, v0
	v_mov_b32_e32 v13, v0
	v_mov_b32_e32 v14, v0
	v_mov_b32_e32 v15, v0
	v_mov_b32_e32 v24, v0
	v_mov_b32_e32 v25, v0
	v_mov_b32_e32 v26, v0
	v_mov_b32_e32 v27, v0
	v_mov_b32_e32 v28, v0
	v_mov_b32_e32 v29, v0
	v_mov_b32_e32 v30, v0
	v_mov_b32_e32 v31, v0
	v_mov_b32_e32 v40, v0
	v_mov_b32_e32 v41, v0
	v_mov_b32_e32 v42, v0
	v_mov_b32_e32 v43, v0
	v_mov_b32_e32 v44, v0
	v_mov_b32_e32 v45, v0
	v_mov_b32_e32 v46, v0
	v_mov_b32_e32 v47, v0
	v_mov_b32_e32 v16, v0
	v_mov_b32_e32 v17, v0
	v_mov_b32_e32 v18, v0
	v_mov_b32_e32 v19, v0
	v_mov_b32_e32 v20, v0
	v_mov_b32_e32 v21, v0
	v_mov_b32_e32 v22, v0
	v_mov_b32_e32 v23, v0
	v_mov_b32_e32 v32, v0
	v_mov_b32_e32 v33, v0
	v_mov_b32_e32 v34, v0
	v_mov_b32_e32 v35, v0
	v_mov_b32_e32 v36, v0
	v_mov_b32_e32 v37, v0
	v_mov_b32_e32 v38, v0
	v_mov_b32_e32 v39, v0
	v_mov_b32_e32 v48, v0
	v_mov_b32_e32 v49, v0
	v_mov_b32_e32 v50, v0
	v_mov_b32_e32 v51, v0
	v_mov_b32_e32 v52, v0
	v_mov_b32_e32 v53, v0
	v_mov_b32_e32 v54, v0
	v_mov_b32_e32 v55, v0
	v_mov_b32_e32 v56, v0
	v_mov_b32_e32 v57, v0
	v_mov_b32_e32 v58, v0
	v_mov_b32_e32 v59, v0
	v_mov_b32_e32 v60, v0
	v_mov_b32_e32 v61, v0
	v_mov_b32_e32 v62, v0
	v_mov_b32_e32 v63, v0
	v_mov_b32_e32 v64, v0
	v_mov_b32_e32 v65, v0
	v_mov_b32_e32 v66, v0
	v_mov_b32_e32 v67, v0
	v_mov_b32_e32 v68, v0
	v_mov_b32_e32 v69, v0
	v_mov_b32_e32 v70, v0
	v_mov_b32_e32 v71, v0
	v_mov_b32_e32 v72, v0
	v_mov_b32_e32 v73, v0
	v_mov_b32_e32 v74, v0
	v_mov_b32_e32 v75, v0
	v_mov_b32_e32 v76, v0
	v_mov_b32_e32 v77, v0
	v_mov_b32_e32 v78, v0
	v_mov_b32_e32 v79, v0
	v_mov_b32_e32 v88, v0
	v_mov_b32_e32 v89, v0
	v_mov_b32_e32 v90, v0
	v_mov_b32_e32 v91, v0
	v_mov_b32_e32 v92, v0
	v_mov_b32_e32 v93, v0
	v_mov_b32_e32 v94, v0
	v_mov_b32_e32 v95, v0
	v_mov_b32_e32 v104, v0
	v_mov_b32_e32 v105, v0
	v_mov_b32_e32 v106, v0
	v_mov_b32_e32 v107, v0
	v_mov_b32_e32 v108, v0
	v_mov_b32_e32 v109, v0
	v_mov_b32_e32 v110, v0
	v_mov_b32_e32 v111, v0
	v_mov_b32_e32 v80, v0
	v_mov_b32_e32 v81, v0
	v_mov_b32_e32 v82, v0
	v_mov_b32_e32 v83, v0
	v_mov_b32_e32 v84, v0
	v_mov_b32_e32 v85, v0
	v_mov_b32_e32 v86, v0
	v_mov_b32_e32 v87, v0
	v_mov_b32_e32 v96, v0
	v_mov_b32_e32 v97, v0
	v_mov_b32_e32 v98, v0
	v_mov_b32_e32 v99, v0
	v_mov_b32_e32 v100, v0
	v_mov_b32_e32 v101, v0
	v_mov_b32_e32 v102, v0
	v_mov_b32_e32 v103, v0
	v_mov_b32_e32 v112, v0
	v_mov_b32_e32 v113, v0
	v_mov_b32_e32 v114, v0
	v_mov_b32_e32 v115, v0
	v_mov_b32_e32 v116, v0
	v_mov_b32_e32 v117, v0
	v_mov_b32_e32 v118, v0
	v_mov_b32_e32 v119, v0
	v_mov_b32_e32 v120, v0
	v_mov_b32_e32 v121, v0
	v_mov_b32_e32 v122, v0
	v_mov_b32_e32 v123, v0
	v_mov_b32_e32 v124, v0
	v_mov_b32_e32 v125, v0
	v_mov_b32_e32 v126, v0
	v_mov_b32_e32 v127, v0
.LBB0_223:
	ds_read_b128 v[146:149], v142
	ds_read_b128 v[150:153], v142 offset:1024
	ds_read_b128 v[154:157], v142 offset:2048
	ds_read_b128 v[158:161], v142 offset:3072
	ds_read_b128 v[162:165], v143
	ds_read_b128 v[166:169], v143 offset:1024
	ds_read_b128 v[170:173], v143 offset:2048
	ds_read_b128 v[174:177], v143 offset:3072
	s_add_u32 s40, s38, 0xfffc0080
	s_addc_u32 s41, s39, -1
	s_cmp_eq_u32 s71, 12
	s_cselect_b32 s45, s35, s41
	s_cselect_b32 s44, s34, s40
	s_cselect_b32 s41, s37, s70
	s_cselect_b32 s40, s36, s69
	v_lshl_add_u64 v[210:211], s[38:39], 0, v[138:139]
	s_add_i32 m0, s54, 0xc000
	ds_read_b128 v[178:181], v144
	ds_read_b128 v[182:185], v144 offset:1024
	ds_read_b128 v[186:189], v144 offset:2048
	ds_read_b128 v[190:193], v144 offset:3072
	ds_read_b128 v[194:197], v144 offset:4096
	ds_read_b128 v[198:201], v144 offset:5120
	ds_read_b128 v[202:205], v144 offset:6144
	ds_read_b128 v[206:209], v144 offset:7168
	global_load_lds_dwordx4 v[210:211], off
	v_lshl_add_u64 v[210:211], s[38:39], 0, v[136:137]
	s_add_i32 m0, s54, 0xe000
	s_nop 0
	global_load_lds_dwordx4 v[210:211], off
	s_waitcnt vmcnt(8)
	s_waitcnt lgkmcnt(0)
	s_barrier
	s_waitcnt lgkmcnt(0)
	v_mfma_f32_16x16x32_bf16 v[124:127], v[146:149], v[178:181], v[124:127]
	v_mfma_f32_16x16x32_bf16 v[120:123], v[154:157], v[178:181], v[120:123]
	v_mfma_f32_16x16x32_bf16 v[116:119], v[146:149], v[186:189], v[116:119]
	v_mfma_f32_16x16x32_bf16 v[112:115], v[154:157], v[186:189], v[112:115]
	v_mfma_f32_16x16x32_bf16 v[100:103], v[146:149], v[194:197], v[100:103]
	v_mfma_f32_16x16x32_bf16 v[96:99], v[154:157], v[194:197], v[96:99]
	v_mfma_f32_16x16x32_bf16 v[84:87], v[146:149], v[202:205], v[84:87]
	v_mfma_f32_16x16x32_bf16 v[80:83], v[154:157], v[202:205], v[80:83]
	v_mfma_f32_16x16x32_bf16 v[124:127], v[150:153], v[182:185], v[124:127]
	v_mfma_f32_16x16x32_bf16 v[120:123], v[158:161], v[182:185], v[120:123]
	v_mfma_f32_16x16x32_bf16 v[116:119], v[150:153], v[190:193], v[116:119]
	v_mfma_f32_16x16x32_bf16 v[112:115], v[158:161], v[190:193], v[112:115]
	v_mfma_f32_16x16x32_bf16 v[100:103], v[150:153], v[198:201], v[100:103]
	v_mfma_f32_16x16x32_bf16 v[96:99], v[158:161], v[198:201], v[96:99]
	v_mfma_f32_16x16x32_bf16 v[84:87], v[150:153], v[206:209], v[84:87]
	v_mfma_f32_16x16x32_bf16 v[80:83], v[158:161], v[206:209], v[80:83]
	v_mfma_f32_16x16x32_bf16 v[108:111], v[162:165], v[178:181], v[108:111]
	v_mfma_f32_16x16x32_bf16 v[104:107], v[170:173], v[178:181], v[104:107]
	v_mfma_f32_16x16x32_bf16 v[92:95], v[162:165], v[186:189], v[92:95]
	v_mfma_f32_16x16x32_bf16 v[88:91], v[170:173], v[186:189], v[88:91]
	v_mfma_f32_16x16x32_bf16 v[76:79], v[162:165], v[194:197], v[76:79]
	v_mfma_f32_16x16x32_bf16 v[72:75], v[170:173], v[194:197], v[72:75]
	v_mfma_f32_16x16x32_bf16 v[68:71], v[162:165], v[202:205], v[68:71]
	v_mfma_f32_16x16x32_bf16 v[64:67], v[170:173], v[202:205], v[64:67]
	v_mfma_f32_16x16x32_bf16 v[108:111], v[166:169], v[182:185], v[108:111]
	v_mfma_f32_16x16x32_bf16 v[104:107], v[174:177], v[182:185], v[104:107]
	v_mfma_f32_16x16x32_bf16 v[92:95], v[166:169], v[190:193], v[92:95]
	v_mfma_f32_16x16x32_bf16 v[88:91], v[174:177], v[190:193], v[88:91]
	v_mfma_f32_16x16x32_bf16 v[76:79], v[166:169], v[198:201], v[76:79]
	v_mfma_f32_16x16x32_bf16 v[72:75], v[174:177], v[198:201], v[72:75]
	v_mfma_f32_16x16x32_bf16 v[68:71], v[166:169], v[206:209], v[68:71]
	v_mfma_f32_16x16x32_bf16 v[64:67], v[174:177], v[206:209], v[64:67]
	s_barrier
; #define PG8_STAGE(bufoff, gbase, voff) do { _Pragma("unroll") for (int _i = 0; _i < 2; ++_i) \
;         __builtin_amdgcn_global_load_lds((const unsigned*)((const char*)(gbase) + (voff)[_i]), (LAS unsigned*)(lds + (bufoff) + ldsw + _i * 8192), 16, 0, 0); } while (0)
; #define PG8_LDA(dst, b, h) do { _Pragma("unroll") for (int m = 0; m < 4; ++m) _Pragma("unroll") for (int k = 0; k < 2; ++k) dst[m][k] = *(const LAS bf16x8*)(lds + PG8_SA(b, h) + aoff + m * 2048 + k * 1024); } while (0)
; #define PG8_LDB(dst, b, h) do { _Pragma("unroll") for (int n = 0; n < 2; ++n) _Pragma("unroll") for (int k = 0; k < 2; ++k) dst[n][k] = *(const LAS bf16x8*)(lds + PG8_SB(b, h) + boff + n * 2048 + k * 1024); } while (0)
; #define PG8_MMA(ai, bj, At, Bt) do { __builtin_amdgcn_s_setprio(1); _Pragma("unroll") for (int m = 0; m < 4; ++m) _Pragma("unroll") for (int n = 0; n < 2; ++n) _Pragma("unroll") for (int k = 0; k < 2; ++k) \
;         acc[ai][bj][m][n] = __builtin_amdgcn_mfma_f32_16x16x32_bf16(Bt[n][k], At[m][k], acc[ai][bj][m][n], 0, 0, 0); __builtin_amdgcn_s_setprio(0); } while (0)
; #define PG8_WAIT_V(n) asm volatile("s_waitcnt vmcnt(" #n ")" ::: "memory")
; #define PG8_WAIT_L(n) asm volatile("s_waitcnt lgkmcnt(" #n ")" ::: "memory")
; #define PG8_BAR __builtin_amdgcn_s_barrier()
; #define PG8_SCHED __builtin_amdgcn_sched_barrier(0)
; template <class Epi, class Sched>
; __device__ __forceinline__ void gemm_phase(LAS unsigned char* lds, const GemmP g, const Sched& S, const Epi& E, int tid) {
;     ...
;             PG8_LDA(At, 0, 1); PG8_STAGE(PG8_SB(0, 0), b2, voffB); PG8_STAGE(PG8_SB(0, 1), b2 + hstepB, voffB); PG8_STAGE(PG8_SA(0, 0), a2, voffA);
;             PG8_WAIT_V(8); PG8_WAIT_L(0); PG8_BAR; PG8_MMA(1, 0, At, B0); PG8_MMA(1, 1, At, B1); PG8_BAR; PG8_SCHED;
;             PG8_LDB(B0, 1, 0); PG8_LDB(B1, 1, 1); PG8_SCHED; PG8_LDA(At, 1, 0); PG8_STAGE(PG8_SA(0, 1), a2 + hstepA, voffA);
;             PG8_WAIT_V(8); PG8_WAIT_L(0); PG8_BAR; PG8_MMA(0, 0, At, B0); PG8_MMA(0, 1, At, B1); PG8_BAR; PG8_SCHED;
	s_add_i32 s72, s63, s53
	v_lshl_add_u64 v[210:211], s[40:41], 0, v[132:133]
	s_mov_b32 m0, s72
	ds_read_b128 v[178:181], v144 offset:16384
	ds_read_b128 v[182:185], v144 offset:17408
	ds_read_b128 v[186:189], v144 offset:18432
	ds_read_b128 v[190:193], v144 offset:19456
	ds_read_b128 v[194:197], v144 offset:20480
	ds_read_b128 v[198:201], v144 offset:21504
	ds_read_b128 v[202:205], v144 offset:22528
	ds_read_b128 v[206:209], v144 offset:23552
	global_load_lds_dwordx4 v[210:211], off
	s_add_i32 m0, s72, 0x2000
	s_add_u32 s72, s40, 0x40000
	v_lshl_add_u64 v[212:213], s[40:41], 0, v[128:129]
	s_addc_u32 s73, s41, 0
	s_add_i32 s74, s64, s53
	global_load_lds_dwordx4 v[212:213], off
	v_lshl_add_u64 v[214:215], s[72:73], 0, v[132:133]
	s_mov_b32 m0, s74
	v_lshl_add_u64 v[216:217], s[44:45], 0, v[130:131]
	global_load_lds_dwordx4 v[214:215], off
	v_lshl_add_u64 v[214:215], s[72:73], 0, v[128:129]
	s_add_i32 m0, s74, 0x2000
	s_nop 0
	global_load_lds_dwordx4 v[214:215], off
	v_lshl_add_u64 v[214:215], s[44:45], 0, v[134:135]
	s_mov_b32 m0, s54
	s_nop 0
	global_load_lds_dwordx4 v[214:215], off
	s_mov_b32 m0, s55
	s_nop 0
	global_load_lds_dwordx4 v[216:217], off
	s_waitcnt vmcnt(8)
	s_waitcnt lgkmcnt(0)
	s_barrier
	s_waitcnt lgkmcnt(0)
	v_mfma_f32_16x16x32_bf16 v[60:63], v[146:149], v[178:181], v[60:63]
	v_mfma_f32_16x16x32_bf16 v[56:59], v[154:157], v[178:181], v[56:59]
	v_mfma_f32_16x16x32_bf16 v[52:55], v[146:149], v[186:189], v[52:55]
	v_mfma_f32_16x16x32_bf16 v[48:51], v[154:157], v[186:189], v[48:51]
	v_mfma_f32_16x16x32_bf16 v[36:39], v[146:149], v[194:197], v[36:39]
	v_mfma_f32_16x16x32_bf16 v[32:35], v[154:157], v[194:197], v[32:35]
	v_mfma_f32_16x16x32_bf16 v[20:23], v[146:149], v[202:205], v[20:23]
	v_mfma_f32_16x16x32_bf16 v[16:19], v[154:157], v[202:205], v[16:19]
	v_mfma_f32_16x16x32_bf16 v[60:63], v[150:153], v[182:185], v[60:63]
	v_mfma_f32_16x16x32_bf16 v[56:59], v[158:161], v[182:185], v[56:59]
	v_mfma_f32_16x16x32_bf16 v[52:55], v[150:153], v[190:193], v[52:55]
	v_mfma_f32_16x16x32_bf16 v[48:51], v[158:161], v[190:193], v[48:51]
	v_mfma_f32_16x16x32_bf16 v[36:39], v[150:153], v[198:201], v[36:39]
	v_mfma_f32_16x16x32_bf16 v[32:35], v[158:161], v[198:201], v[32:35]
	v_mfma_f32_16x16x32_bf16 v[20:23], v[150:153], v[206:209], v[20:23]
	v_mfma_f32_16x16x32_bf16 v[16:19], v[158:161], v[206:209], v[16:19]
	v_mfma_f32_16x16x32_bf16 v[44:47], v[162:165], v[178:181], v[44:47]
	v_mfma_f32_16x16x32_bf16 v[40:43], v[170:173], v[178:181], v[40:43]
	v_mfma_f32_16x16x32_bf16 v[28:31], v[162:165], v[186:189], v[28:31]
	v_mfma_f32_16x16x32_bf16 v[24:27], v[170:173], v[186:189], v[24:27]
	v_mfma_f32_16x16x32_bf16 v[12:15], v[162:165], v[194:197], v[12:15]
	v_mfma_f32_16x16x32_bf16 v[8:11], v[170:173], v[194:197], v[8:11]
	v_mfma_f32_16x16x32_bf16 v[4:7], v[162:165], v[202:205], v[4:7]
	v_mfma_f32_16x16x32_bf16 v[0:3], v[170:173], v[202:205], v[0:3]
	v_mfma_f32_16x16x32_bf16 v[44:47], v[166:169], v[182:185], v[44:47]
	v_mfma_f32_16x16x32_bf16 v[40:43], v[174:177], v[182:185], v[40:43]
	v_mfma_f32_16x16x32_bf16 v[28:31], v[166:169], v[190:193], v[28:31]
	v_mfma_f32_16x16x32_bf16 v[24:27], v[174:177], v[190:193], v[24:27]
	v_mfma_f32_16x16x32_bf16 v[12:15], v[166:169], v[198:201], v[12:15]
	v_mfma_f32_16x16x32_bf16 v[8:11], v[174:177], v[198:201], v[8:11]
	v_mfma_f32_16x16x32_bf16 v[4:7], v[166:169], v[206:209], v[4:7]
	v_mfma_f32_16x16x32_bf16 v[0:3], v[174:177], v[206:209], v[0:3]
	s_barrier
	s_add_i32 s72, 0, 0x18000
	v_add_u32_e32 v145, s72, v141
	s_add_i32 s73, 0, 0x1c000
	ds_read_b128 v[146:149], v145
	ds_read_b128 v[150:153], v145 offset:1024
	ds_read_b128 v[154:157], v145 offset:2048
	ds_read_b128 v[158:161], v145 offset:3072
	v_add_u32_e32 v145, s73, v141
	ds_read_b128 v[162:165], v145
	ds_read_b128 v[166:169], v145 offset:1024
	ds_read_b128 v[170:173], v145 offset:2048
	ds_read_b128 v[174:177], v145 offset:3072
	s_add_u32 s44, s44, 0x40000
	s_addc_u32 s45, s45, 0
	s_mov_b32 m0, s56
	v_lshl_add_u64 v[218:219], s[44:45], 0, v[134:135]
	ds_read_b128 v[178:181], v144 offset:32768
	ds_read_b128 v[182:185], v144 offset:33792
	ds_read_b128 v[186:189], v144 offset:34816
	ds_read_b128 v[190:193], v144 offset:35840
	ds_read_b128 v[194:197], v144 offset:36864
	ds_read_b128 v[198:201], v144 offset:37888
	ds_read_b128 v[202:205], v144 offset:38912
	ds_read_b128 v[206:209], v144 offset:39936
	global_load_lds_dwordx4 v[218:219], off
	v_lshl_add_u64 v[218:219], s[44:45], 0, v[130:131]
	s_mov_b32 m0, s57
	s_nop 0
	global_load_lds_dwordx4 v[218:219], off
	s_waitcnt vmcnt(8)
	s_waitcnt lgkmcnt(0)
	s_barrier
; #define PG8_STAGE(bufoff, gbase, voff) do { _Pragma("unroll") for (int _i = 0; _i < 2; ++_i) \
;         __builtin_amdgcn_global_load_lds((const unsigned*)((const char*)(gbase) + (voff)[_i]), (LAS unsigned*)(lds + (bufoff) + ldsw + _i * 8192), 16, 0, 0); } while (0)
; #define PG8_LDA(dst, b, h) do { _Pragma("unroll") for (int m = 0; m < 4; ++m) _Pragma("unroll") for (int k = 0; k < 2; ++k) dst[m][k] = *(const LAS bf16x8*)(lds + PG8_SA(b, h) + aoff + m * 2048 + k * 1024); } while (0)
; #define PG8_MMA(ai, bj, At, Bt) do { __builtin_amdgcn_s_setprio(1); _Pragma("unroll") for (int m = 0; m < 4; ++m) _Pragma("unroll") for (int n = 0; n < 2; ++n) _Pragma("unroll") for (int k = 0; k < 2; ++k) \
;         acc[ai][bj][m][n] = __builtin_amdgcn_mfma_f32_16x16x32_bf16(Bt[n][k], At[m][k], acc[ai][bj][m][n], 0, 0, 0); __builtin_amdgcn_s_setprio(0); } while (0)
; #define PG8_WAIT_V(n) asm volatile("s_waitcnt vmcnt(" #n ")" ::: "memory")
; #define PG8_WAIT_L(n) asm volatile("s_waitcnt lgkmcnt(" #n ")" ::: "memory")
; #define PG8_BAR __builtin_amdgcn_s_barrier()
; #define PG8_SCHED __builtin_amdgcn_sched_barrier(0)
; template <class Epi, class Sched>
; __device__ __forceinline__ void gemm_phase(LAS unsigned char* lds, const GemmP g, const Sched& S, const Epi& E, int tid) {
;     ...
;             PG8_WAIT_V(8); PG8_WAIT_L(0); PG8_BAR; PG8_MMA(0, 0, At, B0); PG8_MMA(0, 1, At, B1); PG8_BAR; PG8_SCHED;
;             PG8_LDA(At, 1, 1); PG8_STAGE(PG8_SB(1, 0), b3, voffB); PG8_STAGE(PG8_SB(1, 1), b3 + hstepB, voffB); PG8_STAGE(PG8_SA(1, 0), a3, voffA);
;             PG8_WAIT_V(8); PG8_WAIT_L(0); PG8_BAR; PG8_MMA(1, 0, At, B0); PG8_MMA(1, 1, At, B1); PG8_BAR; PG8_SCHED;
;         }
;         if (wr == 0) PG8_BAR;
	s_waitcnt lgkmcnt(0)
	v_mfma_f32_16x16x32_bf16 v[124:127], v[146:149], v[178:181], v[124:127]
	v_mfma_f32_16x16x32_bf16 v[120:123], v[154:157], v[178:181], v[120:123]
	v_mfma_f32_16x16x32_bf16 v[116:119], v[146:149], v[186:189], v[116:119]
	v_mfma_f32_16x16x32_bf16 v[112:115], v[154:157], v[186:189], v[112:115]
	v_mfma_f32_16x16x32_bf16 v[100:103], v[146:149], v[194:197], v[100:103]
	v_mfma_f32_16x16x32_bf16 v[96:99], v[154:157], v[194:197], v[96:99]
	v_mfma_f32_16x16x32_bf16 v[84:87], v[146:149], v[202:205], v[84:87]
	v_mfma_f32_16x16x32_bf16 v[80:83], v[154:157], v[202:205], v[80:83]
	v_mfma_f32_16x16x32_bf16 v[124:127], v[150:153], v[182:185], v[124:127]
	v_mfma_f32_16x16x32_bf16 v[120:123], v[158:161], v[182:185], v[120:123]
	v_mfma_f32_16x16x32_bf16 v[116:119], v[150:153], v[190:193], v[116:119]
	v_mfma_f32_16x16x32_bf16 v[112:115], v[158:161], v[190:193], v[112:115]
	v_mfma_f32_16x16x32_bf16 v[100:103], v[150:153], v[198:201], v[100:103]
	v_mfma_f32_16x16x32_bf16 v[96:99], v[158:161], v[198:201], v[96:99]
	v_mfma_f32_16x16x32_bf16 v[84:87], v[150:153], v[206:209], v[84:87]
	v_mfma_f32_16x16x32_bf16 v[80:83], v[158:161], v[206:209], v[80:83]
	v_mfma_f32_16x16x32_bf16 v[108:111], v[162:165], v[178:181], v[108:111]
	v_mfma_f32_16x16x32_bf16 v[104:107], v[170:173], v[178:181], v[104:107]
	v_mfma_f32_16x16x32_bf16 v[92:95], v[162:165], v[186:189], v[92:95]
	v_mfma_f32_16x16x32_bf16 v[88:91], v[170:173], v[186:189], v[88:91]
	v_mfma_f32_16x16x32_bf16 v[76:79], v[162:165], v[194:197], v[76:79]
	v_mfma_f32_16x16x32_bf16 v[72:75], v[170:173], v[194:197], v[72:75]
	v_mfma_f32_16x16x32_bf16 v[68:71], v[162:165], v[202:205], v[68:71]
	v_mfma_f32_16x16x32_bf16 v[64:67], v[170:173], v[202:205], v[64:67]
	v_mfma_f32_16x16x32_bf16 v[108:111], v[166:169], v[182:185], v[108:111]
	v_mfma_f32_16x16x32_bf16 v[104:107], v[174:177], v[182:185], v[104:107]
	v_mfma_f32_16x16x32_bf16 v[92:95], v[166:169], v[190:193], v[92:95]
	v_mfma_f32_16x16x32_bf16 v[88:91], v[174:177], v[190:193], v[88:91]
	v_mfma_f32_16x16x32_bf16 v[76:79], v[166:169], v[198:201], v[76:79]
	v_mfma_f32_16x16x32_bf16 v[72:75], v[174:177], v[198:201], v[72:75]
	v_mfma_f32_16x16x32_bf16 v[68:71], v[166:169], v[206:209], v[68:71]
	v_mfma_f32_16x16x32_bf16 v[64:67], v[174:177], v[206:209], v[64:67]
	s_barrier
	s_add_i32 s44, s72, s53
	v_lshl_add_u64 v[210:211], v[210:211], 0, s[12:13]
	s_mov_b32 m0, s44
	ds_read_b128 v[178:181], v144 offset:49152
	ds_read_b128 v[182:185], v144 offset:50176
	ds_read_b128 v[186:189], v144 offset:51200
	ds_read_b128 v[190:193], v144 offset:52224
	ds_read_b128 v[194:197], v144 offset:53248
	ds_read_b128 v[198:201], v144 offset:54272
	ds_read_b128 v[202:205], v144 offset:55296
	ds_read_b128 v[206:209], v144 offset:56320
	global_load_lds_dwordx4 v[210:211], off
	s_add_i32 m0, s44, 0x2000
	s_add_u32 s40, s40, 0x40080
	v_lshl_add_u64 v[210:211], v[212:213], 0, s[12:13]
	s_addc_u32 s41, s41, 0
	s_add_i32 s44, s73, s53
	global_load_lds_dwordx4 v[210:211], off
	v_lshl_add_u64 v[210:211], s[40:41], 0, v[132:133]
	s_mov_b32 m0, s44
	s_nop 0
	global_load_lds_dwordx4 v[210:211], off
	v_lshl_add_u64 v[210:211], s[40:41], 0, v[128:129]
	s_add_i32 m0, s44, 0x2000
	s_nop 0
	global_load_lds_dwordx4 v[210:211], off
	v_lshl_add_u64 v[210:211], v[214:215], 0, s[12:13]
	s_mov_b32 m0, s61
	s_nop 0
	global_load_lds_dwordx4 v[210:211], off
	v_lshl_add_u64 v[210:211], v[216:217], 0, s[12:13]
	s_mov_b32 m0, s62
	s_nop 0
	global_load_lds_dwordx4 v[210:211], off
	s_waitcnt vmcnt(8)
	s_waitcnt lgkmcnt(0)
	s_barrier
	s_waitcnt lgkmcnt(0)
	v_mfma_f32_16x16x32_bf16 v[60:63], v[146:149], v[178:181], v[60:63]
	v_mfma_f32_16x16x32_bf16 v[56:59], v[154:157], v[178:181], v[56:59]
	v_mfma_f32_16x16x32_bf16 v[52:55], v[146:149], v[186:189], v[52:55]
	v_mfma_f32_16x16x32_bf16 v[48:51], v[154:157], v[186:189], v[48:51]
	v_mfma_f32_16x16x32_bf16 v[36:39], v[146:149], v[194:197], v[36:39]
	v_mfma_f32_16x16x32_bf16 v[32:35], v[154:157], v[194:197], v[32:35]
	v_mfma_f32_16x16x32_bf16 v[20:23], v[146:149], v[202:205], v[20:23]
	v_mfma_f32_16x16x32_bf16 v[16:19], v[154:157], v[202:205], v[16:19]
	v_mfma_f32_16x16x32_bf16 v[60:63], v[150:153], v[182:185], v[60:63]
	v_mfma_f32_16x16x32_bf16 v[56:59], v[158:161], v[182:185], v[56:59]
	v_mfma_f32_16x16x32_bf16 v[52:55], v[150:153], v[190:193], v[52:55]
	v_mfma_f32_16x16x32_bf16 v[48:51], v[158:161], v[190:193], v[48:51]
	v_mfma_f32_16x16x32_bf16 v[36:39], v[150:153], v[198:201], v[36:39]
	v_mfma_f32_16x16x32_bf16 v[32:35], v[158:161], v[198:201], v[32:35]
	v_mfma_f32_16x16x32_bf16 v[20:23], v[150:153], v[206:209], v[20:23]
	v_mfma_f32_16x16x32_bf16 v[16:19], v[158:161], v[206:209], v[16:19]
	v_mfma_f32_16x16x32_bf16 v[44:47], v[162:165], v[178:181], v[44:47]
	v_mfma_f32_16x16x32_bf16 v[40:43], v[170:173], v[178:181], v[40:43]
	v_mfma_f32_16x16x32_bf16 v[28:31], v[162:165], v[186:189], v[28:31]
	v_mfma_f32_16x16x32_bf16 v[24:27], v[170:173], v[186:189], v[24:27]
	v_mfma_f32_16x16x32_bf16 v[12:15], v[162:165], v[194:197], v[12:15]
	v_mfma_f32_16x16x32_bf16 v[8:11], v[170:173], v[194:197], v[8:11]
	v_mfma_f32_16x16x32_bf16 v[4:7], v[162:165], v[202:205], v[4:7]
	v_mfma_f32_16x16x32_bf16 v[0:3], v[170:173], v[202:205], v[0:3]
	v_mfma_f32_16x16x32_bf16 v[44:47], v[166:169], v[182:185], v[44:47]
	v_mfma_f32_16x16x32_bf16 v[40:43], v[174:177], v[182:185], v[40:43]
	v_mfma_f32_16x16x32_bf16 v[28:31], v[166:169], v[190:193], v[28:31]
	v_mfma_f32_16x16x32_bf16 v[24:27], v[174:177], v[190:193], v[24:27]
	v_mfma_f32_16x16x32_bf16 v[12:15], v[166:169], v[198:201], v[12:15]
	v_mfma_f32_16x16x32_bf16 v[8:11], v[174:177], v[198:201], v[8:11]
	v_mfma_f32_16x16x32_bf16 v[4:7], v[166:169], v[206:209], v[4:7]
	v_mfma_f32_16x16x32_bf16 v[0:3], v[174:177], v[206:209], v[0:3]
	s_barrier
	s_add_i32 s71, s71, 2
	s_add_u32 s69, s69, 0x100
	s_addc_u32 s70, s70, 0
	s_add_u32 s38, s38, 0x100
	s_addc_u32 s39, s39, 0
	s_cmp_gt_u32 s71, 13
	s_cbranch_scc0 .LBB0_223
	s_setprio 0
	s_and_b64 vcc, exec, s[14:15]
	s_cbranch_vccz .LBB0_226
	s_barrier

; #define PG8_STAGE(bufoff, gbase, voff) do { _Pragma("unroll") for (int _i = 0; _i < 2; ++_i) \
;         __builtin_amdgcn_global_load_lds((const unsigned*)((const char*)(gbase) + (voff)[_i]), (LAS unsigned*)(lds + (bufoff) + ldsw + _i * 8192), 16, 0, 0); } while (0)
; #define PG8_LDA(dst, b, h) do { _Pragma("unroll") for (int m = 0; m < 4; ++m) _Pragma("unroll") for (int k = 0; k < 2; ++k) dst[m][k] = *(const LAS bf16x8*)(lds + PG8_SA(b, h) + aoff + m * 2048 + k * 1024); } while (0)
; #define PG8_LDB(dst, b, h) do { _Pragma("unroll") for (int n = 0; n < 2; ++n) _Pragma("unroll") for (int k = 0; k < 2; ++k) dst[n][k] = *(const LAS bf16x8*)(lds + PG8_SB(b, h) + boff + n * 2048 + k * 1024); } while (0)
; #define PG8_MMA(ai, bj, At, Bt) do { __builtin_amdgcn_s_setprio(1); _Pragma("unroll") for (int m = 0; m < 4; ++m) _Pragma("unroll") for (int n = 0; n < 2; ++n) _Pragma("unroll") for (int k = 0; k < 2; ++k) \
;         acc[ai][bj][m][n] = __builtin_amdgcn_mfma_f32_16x16x32_bf16(Bt[n][k], At[m][k], acc[ai][bj][m][n], 0, 0, 0); __builtin_amdgcn_s_setprio(0); } while (0)
; #define PG8_WAIT_V(n) asm volatile("s_waitcnt vmcnt(" #n ")" ::: "memory")
; #define PG8_WAIT_L(n) asm volatile("s_waitcnt lgkmcnt(" #n ")" ::: "memory")
; #define PG8_BAR __builtin_amdgcn_s_barrier()
; template <class Epi, class Sched>
; __device__ __forceinline__ void gemm_phase(LAS unsigned char* lds, const GemmP g, const Sched& S, const Epi& E, int tid) {
;     ...
;         for (int t = 0; t < nt; t += 2) {
;             const bool last = (t == nt - 2);
;             const char* a1 = cA + (size_t)(t + 1) * kstep;
;             const char* a2 = last ? nA : cA + (size_t)(t + 2) * kstep; const char* b2 = last ? nB : cB + (size_t)(t + 2) * kstep;
;             const char* a3 = a2 + kstep; const char* b3 = b2 + kstep;
;             PG8_LDB(B0, 0, 0); PG8_LDB(B1, 0, 1); PG8_SCHED; PG8_LDA(At, 0, 0); PG8_STAGE(PG8_SA(1, 1), a1 + hstepA, voffA);
;             PG8_WAIT_V(8); PG8_WAIT_L(0); PG8_BAR; PG8_MMA(0, 0, At, B0); PG8_MMA(0, 1, At, B1); PG8_BAR; PG8_SCHED;
;     ...
; #pragma unroll
;         for (int a = 0; a < 2; ++a)
; #pragma unroll
;             for (int b = 0; b < 2; ++b)
; #pragma unroll
;                 for (int m = 0; m < 4; ++m)
; #pragma unroll
;                     for (int n = 0; n < 2; ++n) acc[a][b][m][n] = (f32x4){0.f, 0.f, 0.f, 0.f};
;         cur = nxt; cA = nA; cB = nB; ++ui;
.LBB0_242:
	s_add_u32 s62, s38, 0x100
	s_addc_u32 s63, s39, 0
	s_add_u32 s36, s36, 0x40080
	v_mov_b32_e32 v0, 0
	s_addc_u32 s37, s37, 0
	s_mov_b32 s64, -2
	v_mov_b32_e32 v1, v0
	v_mov_b32_e32 v2, v0
	v_mov_b32_e32 v3, v0
	v_mov_b32_e32 v4, v0
	v_mov_b32_e32 v5, v0
	v_mov_b32_e32 v6, v0
	v_mov_b32_e32 v7, v0
	v_mov_b32_e32 v8, v0
	v_mov_b32_e32 v9, v0
	v_mov_b32_e32 v10, v0
	v_mov_b32_e32 v11, v0
	v_mov_b32_e32 v12, v0
	v_mov_b32_e32 v13, v0
	v_mov_b32_e32 v14, v0
	v_mov_b32_e32 v15, v0
	v_mov_b32_e32 v24, v0
	v_mov_b32_e32 v25, v0
	v_mov_b32_e32 v26, v0
	v_mov_b32_e32 v27, v0
	v_mov_b32_e32 v28, v0
	v_mov_b32_e32 v29, v0
	v_mov_b32_e32 v30, v0
	v_mov_b32_e32 v31, v0
	v_mov_b32_e32 v40, v0
	v_mov_b32_e32 v41, v0
	v_mov_b32_e32 v42, v0
	v_mov_b32_e32 v43, v0
	v_mov_b32_e32 v44, v0
	v_mov_b32_e32 v45, v0
	v_mov_b32_e32 v46, v0
	v_mov_b32_e32 v47, v0
	v_mov_b32_e32 v16, v0
	v_mov_b32_e32 v17, v0
	v_mov_b32_e32 v18, v0
	v_mov_b32_e32 v19, v0
	v_mov_b32_e32 v20, v0
	v_mov_b32_e32 v21, v0
	v_mov_b32_e32 v22, v0
	v_mov_b32_e32 v23, v0
	v_mov_b32_e32 v32, v0
	v_mov_b32_e32 v33, v0
	v_mov_b32_e32 v34, v0
	v_mov_b32_e32 v35, v0
	v_mov_b32_e32 v36, v0
	v_mov_b32_e32 v37, v0
	v_mov_b32_e32 v38, v0
	v_mov_b32_e32 v39, v0
	v_mov_b32_e32 v48, v0
	v_mov_b32_e32 v49, v0
	v_mov_b32_e32 v50, v0
	v_mov_b32_e32 v51, v0
	v_mov_b32_e32 v52, v0
	v_mov_b32_e32 v53, v0
	v_mov_b32_e32 v54, v0
	v_mov_b32_e32 v55, v0
	v_mov_b32_e32 v56, v0
	v_mov_b32_e32 v57, v0
	v_mov_b32_e32 v58, v0
	v_mov_b32_e32 v59, v0
	v_mov_b32_e32 v60, v0
	v_mov_b32_e32 v61, v0
	v_mov_b32_e32 v62, v0
	v_mov_b32_e32 v63, v0
	v_mov_b32_e32 v64, v0
	v_mov_b32_e32 v65, v0
	v_mov_b32_e32 v66, v0
	v_mov_b32_e32 v67, v0
	v_mov_b32_e32 v68, v0
	v_mov_b32_e32 v69, v0
	v_mov_b32_e32 v70, v0
	v_mov_b32_e32 v71, v0
	v_mov_b32_e32 v72, v0
	v_mov_b32_e32 v73, v0
	v_mov_b32_e32 v74, v0
	v_mov_b32_e32 v75, v0
	v_mov_b32_e32 v76, v0
	v_mov_b32_e32 v77, v0
	v_mov_b32_e32 v78, v0
	v_mov_b32_e32 v79, v0
	v_mov_b32_e32 v88, v0
	v_mov_b32_e32 v89, v0
	v_mov_b32_e32 v90, v0
	v_mov_b32_e32 v91, v0
	v_mov_b32_e32 v92, v0
	v_mov_b32_e32 v93, v0
	v_mov_b32_e32 v94, v0
	v_mov_b32_e32 v95, v0
	v_mov_b32_e32 v104, v0
	v_mov_b32_e32 v105, v0
	v_mov_b32_e32 v106, v0
	v_mov_b32_e32 v107, v0
	v_mov_b32_e32 v108, v0
	v_mov_b32_e32 v109, v0
	v_mov_b32_e32 v110, v0
	v_mov_b32_e32 v111, v0
	v_mov_b32_e32 v80, v0
	v_mov_b32_e32 v81, v0
	v_mov_b32_e32 v82, v0
	v_mov_b32_e32 v83, v0
	v_mov_b32_e32 v84, v0
	v_mov_b32_e32 v85, v0
	v_mov_b32_e32 v86, v0
	v_mov_b32_e32 v87, v0
	v_mov_b32_e32 v96, v0
	v_mov_b32_e32 v97, v0
	v_mov_b32_e32 v98, v0
	v_mov_b32_e32 v99, v0
	v_mov_b32_e32 v100, v0
	v_mov_b32_e32 v101, v0
	v_mov_b32_e32 v102, v0
	v_mov_b32_e32 v103, v0
	v_mov_b32_e32 v112, v0
	v_mov_b32_e32 v113, v0
	v_mov_b32_e32 v114, v0
	v_mov_b32_e32 v115, v0
	v_mov_b32_e32 v116, v0
	v_mov_b32_e32 v117, v0
	v_mov_b32_e32 v118, v0
	v_mov_b32_e32 v119, v0
	v_mov_b32_e32 v120, v0
	v_mov_b32_e32 v121, v0
	v_mov_b32_e32 v122, v0
	v_mov_b32_e32 v123, v0
	v_mov_b32_e32 v124, v0
	v_mov_b32_e32 v125, v0
	v_mov_b32_e32 v126, v0
	v_mov_b32_e32 v127, v0
.LBB0_243:
	ds_read_b128 v[144:147], v141
	ds_read_b128 v[148:151], v141 offset:1024
	ds_read_b128 v[152:155], v141 offset:2048
	ds_read_b128 v[156:159], v141 offset:3072
	ds_read_b128 v[160:163], v142
	ds_read_b128 v[164:167], v142 offset:1024
	ds_read_b128 v[168:171], v142 offset:2048
	ds_read_b128 v[172:175], v142 offset:3072
	s_add_u32 s38, s36, 0xfffc0080
	s_addc_u32 s39, s37, -1
	s_cmp_eq_u32 s64, 12
	s_cselect_b32 s41, s31, s39
	s_cselect_b32 s40, s30, s38
	s_cselect_b32 s39, s35, s63
	s_cselect_b32 s38, s34, s62
	v_lshl_add_u64 v[208:209], s[36:37], 0, v[138:139]
	s_add_i32 m0, s49, 0xc000
	ds_read_b128 v[176:179], v143
	ds_read_b128 v[180:183], v143 offset:1024
	ds_read_b128 v[184:187], v143 offset:2048
	ds_read_b128 v[188:191], v143 offset:3072
	ds_read_b128 v[192:195], v143 offset:4096
	ds_read_b128 v[196:199], v143 offset:5120
	ds_read_b128 v[200:203], v143 offset:6144
	ds_read_b128 v[204:207], v143 offset:7168
	global_load_lds_dwordx4 v[208:209], off
	v_lshl_add_u64 v[208:209], s[36:37], 0, v[136:137]
	s_add_i32 m0, s49, 0xe000
	s_nop 0
	global_load_lds_dwordx4 v[208:209], off
	s_waitcnt vmcnt(8)
	s_waitcnt lgkmcnt(0)
	s_barrier
	s_waitcnt lgkmcnt(0)
	v_mfma_f32_16x16x32_bf16 v[124:127], v[144:147], v[176:179], v[124:127]
	v_mfma_f32_16x16x32_bf16 v[120:123], v[152:155], v[176:179], v[120:123]
	v_mfma_f32_16x16x32_bf16 v[116:119], v[144:147], v[184:187], v[116:119]
	v_mfma_f32_16x16x32_bf16 v[112:115], v[152:155], v[184:187], v[112:115]
	v_mfma_f32_16x16x32_bf16 v[100:103], v[144:147], v[192:195], v[100:103]
	v_mfma_f32_16x16x32_bf16 v[96:99], v[152:155], v[192:195], v[96:99]
	v_mfma_f32_16x16x32_bf16 v[84:87], v[144:147], v[200:203], v[84:87]
	v_mfma_f32_16x16x32_bf16 v[80:83], v[152:155], v[200:203], v[80:83]
	v_mfma_f32_16x16x32_bf16 v[124:127], v[148:151], v[180:183], v[124:127]
	v_mfma_f32_16x16x32_bf16 v[120:123], v[156:159], v[180:183], v[120:123]
	v_mfma_f32_16x16x32_bf16 v[116:119], v[148:151], v[188:191], v[116:119]
	v_mfma_f32_16x16x32_bf16 v[112:115], v[156:159], v[188:191], v[112:115]
	v_mfma_f32_16x16x32_bf16 v[100:103], v[148:151], v[196:199], v[100:103]
	v_mfma_f32_16x16x32_bf16 v[96:99], v[156:159], v[196:199], v[96:99]
	v_mfma_f32_16x16x32_bf16 v[84:87], v[148:151], v[204:207], v[84:87]
	v_mfma_f32_16x16x32_bf16 v[80:83], v[156:159], v[204:207], v[80:83]
	v_mfma_f32_16x16x32_bf16 v[108:111], v[160:163], v[176:179], v[108:111]
	v_mfma_f32_16x16x32_bf16 v[104:107], v[168:171], v[176:179], v[104:107]
	v_mfma_f32_16x16x32_bf16 v[92:95], v[160:163], v[184:187], v[92:95]
	v_mfma_f32_16x16x32_bf16 v[88:91], v[168:171], v[184:187], v[88:91]
	v_mfma_f32_16x16x32_bf16 v[76:79], v[160:163], v[192:195], v[76:79]
	v_mfma_f32_16x16x32_bf16 v[72:75], v[168:171], v[192:195], v[72:75]
	v_mfma_f32_16x16x32_bf16 v[68:71], v[160:163], v[200:203], v[68:71]
	v_mfma_f32_16x16x32_bf16 v[64:67], v[168:171], v[200:203], v[64:67]
	v_mfma_f32_16x16x32_bf16 v[108:111], v[164:167], v[180:183], v[108:111]
	v_mfma_f32_16x16x32_bf16 v[104:107], v[172:175], v[180:183], v[104:107]
	v_mfma_f32_16x16x32_bf16 v[92:95], v[164:167], v[188:191], v[92:95]
	v_mfma_f32_16x16x32_bf16 v[88:91], v[172:175], v[188:191], v[88:91]
	v_mfma_f32_16x16x32_bf16 v[76:79], v[164:167], v[196:199], v[76:79]
	v_mfma_f32_16x16x32_bf16 v[72:75], v[172:175], v[196:199], v[72:75]
	v_mfma_f32_16x16x32_bf16 v[68:71], v[164:167], v[204:207], v[68:71]
	v_mfma_f32_16x16x32_bf16 v[64:67], v[172:175], v[204:207], v[64:67]
	s_barrier
; #define PG8_STAGE(bufoff, gbase, voff) do { _Pragma("unroll") for (int _i = 0; _i < 2; ++_i) \
;         __builtin_amdgcn_global_load_lds((const unsigned*)((const char*)(gbase) + (voff)[_i]), (LAS unsigned*)(lds + (bufoff) + ldsw + _i * 8192), 16, 0, 0); } while (0)
; #define PG8_LDA(dst, b, h) do { _Pragma("unroll") for (int m = 0; m < 4; ++m) _Pragma("unroll") for (int k = 0; k < 2; ++k) dst[m][k] = *(const LAS bf16x8*)(lds + PG8_SA(b, h) + aoff + m * 2048 + k * 1024); } while (0)
; #define PG8_LDB(dst, b, h) do { _Pragma("unroll") for (int n = 0; n < 2; ++n) _Pragma("unroll") for (int k = 0; k < 2; ++k) dst[n][k] = *(const LAS bf16x8*)(lds + PG8_SB(b, h) + boff + n * 2048 + k * 1024); } while (0)
; #define PG8_MMA(ai, bj, At, Bt) do { __builtin_amdgcn_s_setprio(1); _Pragma("unroll") for (int m = 0; m < 4; ++m) _Pragma("unroll") for (int n = 0; n < 2; ++n) _Pragma("unroll") for (int k = 0; k < 2; ++k) \
;         acc[ai][bj][m][n] = __builtin_amdgcn_mfma_f32_16x16x32_bf16(Bt[n][k], At[m][k], acc[ai][bj][m][n], 0, 0, 0); __builtin_amdgcn_s_setprio(0); } while (0)
; #define PG8_WAIT_V(n) asm volatile("s_waitcnt vmcnt(" #n ")" ::: "memory")
; #define PG8_WAIT_L(n) asm volatile("s_waitcnt lgkmcnt(" #n ")" ::: "memory")
; #define PG8_BAR __builtin_amdgcn_s_barrier()
; #define PG8_SCHED __builtin_amdgcn_sched_barrier(0)
; template <class Epi, class Sched>
; __device__ __forceinline__ void gemm_phase(LAS unsigned char* lds, const GemmP g, const Sched& S, const Epi& E, int tid) {
;     ...
;             PG8_LDA(At, 0, 1); PG8_STAGE(PG8_SB(0, 0), b2, voffB); PG8_STAGE(PG8_SB(0, 1), b2 + hstepB, voffB); PG8_STAGE(PG8_SA(0, 0), a2, voffA);
;             PG8_WAIT_V(8); PG8_WAIT_L(0); PG8_BAR; PG8_MMA(1, 0, At, B0); PG8_MMA(1, 1, At, B1); PG8_BAR; PG8_SCHED;
;             PG8_LDB(B0, 1, 0); PG8_LDB(B1, 1, 1); PG8_SCHED; PG8_LDA(At, 1, 0); PG8_STAGE(PG8_SA(0, 1), a2 + hstepA, voffA);
;             PG8_WAIT_V(8); PG8_WAIT_L(0); PG8_BAR; PG8_MMA(0, 0, At, B0); PG8_MMA(0, 1, At, B1); PG8_BAR; PG8_SCHED;
	s_add_i32 s65, s56, s48
	v_lshl_add_u64 v[208:209], s[38:39], 0, v[132:133]
	s_mov_b32 m0, s65
	ds_read_b128 v[176:179], v143 offset:16384
	ds_read_b128 v[180:183], v143 offset:17408
	ds_read_b128 v[184:187], v143 offset:18432
	ds_read_b128 v[188:191], v143 offset:19456
	ds_read_b128 v[192:195], v143 offset:20480
	ds_read_b128 v[196:199], v143 offset:21504
	ds_read_b128 v[200:203], v143 offset:22528
	ds_read_b128 v[204:207], v143 offset:23552
	global_load_lds_dwordx4 v[208:209], off
	s_add_i32 m0, s65, 0x2000
	s_add_u32 s66, s38, 0x40000
	v_lshl_add_u64 v[210:211], s[38:39], 0, v[128:129]
	s_addc_u32 s67, s39, 0
	s_add_i32 s65, s57, s48
	global_load_lds_dwordx4 v[210:211], off
	v_lshl_add_u64 v[212:213], s[66:67], 0, v[132:133]
	s_mov_b32 m0, s65
	v_lshl_add_u64 v[214:215], s[40:41], 0, v[130:131]
	global_load_lds_dwordx4 v[212:213], off
	v_lshl_add_u64 v[212:213], s[66:67], 0, v[128:129]
	s_add_i32 m0, s65, 0x2000
	s_nop 0
	global_load_lds_dwordx4 v[212:213], off
	v_lshl_add_u64 v[212:213], s[40:41], 0, v[134:135]
	s_mov_b32 m0, s49
	s_nop 0
	global_load_lds_dwordx4 v[212:213], off
	s_mov_b32 m0, s50
	s_nop 0
	global_load_lds_dwordx4 v[214:215], off
	s_waitcnt vmcnt(8)
	s_waitcnt lgkmcnt(0)
	s_barrier
	s_waitcnt lgkmcnt(0)
	v_mfma_f32_16x16x32_bf16 v[60:63], v[144:147], v[176:179], v[60:63]
	v_mfma_f32_16x16x32_bf16 v[56:59], v[152:155], v[176:179], v[56:59]
	v_mfma_f32_16x16x32_bf16 v[52:55], v[144:147], v[184:187], v[52:55]
	v_mfma_f32_16x16x32_bf16 v[48:51], v[152:155], v[184:187], v[48:51]
	v_mfma_f32_16x16x32_bf16 v[36:39], v[144:147], v[192:195], v[36:39]
	v_mfma_f32_16x16x32_bf16 v[32:35], v[152:155], v[192:195], v[32:35]
	v_mfma_f32_16x16x32_bf16 v[20:23], v[144:147], v[200:203], v[20:23]
	v_mfma_f32_16x16x32_bf16 v[16:19], v[152:155], v[200:203], v[16:19]
	v_mfma_f32_16x16x32_bf16 v[60:63], v[148:151], v[180:183], v[60:63]
	v_mfma_f32_16x16x32_bf16 v[56:59], v[156:159], v[180:183], v[56:59]
	v_mfma_f32_16x16x32_bf16 v[52:55], v[148:151], v[188:191], v[52:55]
	v_mfma_f32_16x16x32_bf16 v[48:51], v[156:159], v[188:191], v[48:51]
	v_mfma_f32_16x16x32_bf16 v[36:39], v[148:151], v[196:199], v[36:39]
	v_mfma_f32_16x16x32_bf16 v[32:35], v[156:159], v[196:199], v[32:35]
	v_mfma_f32_16x16x32_bf16 v[20:23], v[148:151], v[204:207], v[20:23]
	v_mfma_f32_16x16x32_bf16 v[16:19], v[156:159], v[204:207], v[16:19]
	v_mfma_f32_16x16x32_bf16 v[44:47], v[160:163], v[176:179], v[44:47]
	v_mfma_f32_16x16x32_bf16 v[40:43], v[168:171], v[176:179], v[40:43]
	v_mfma_f32_16x16x32_bf16 v[28:31], v[160:163], v[184:187], v[28:31]
	v_mfma_f32_16x16x32_bf16 v[24:27], v[168:171], v[184:187], v[24:27]
	v_mfma_f32_16x16x32_bf16 v[12:15], v[160:163], v[192:195], v[12:15]
	v_mfma_f32_16x16x32_bf16 v[8:11], v[168:171], v[192:195], v[8:11]
	v_mfma_f32_16x16x32_bf16 v[4:7], v[160:163], v[200:203], v[4:7]
	v_mfma_f32_16x16x32_bf16 v[0:3], v[168:171], v[200:203], v[0:3]
	v_mfma_f32_16x16x32_bf16 v[44:47], v[164:167], v[180:183], v[44:47]
	v_mfma_f32_16x16x32_bf16 v[40:43], v[172:175], v[180:183], v[40:43]
	v_mfma_f32_16x16x32_bf16 v[28:31], v[164:167], v[188:191], v[28:31]
	v_mfma_f32_16x16x32_bf16 v[24:27], v[172:175], v[188:191], v[24:27]
	v_mfma_f32_16x16x32_bf16 v[12:15], v[164:167], v[196:199], v[12:15]
	v_mfma_f32_16x16x32_bf16 v[8:11], v[172:175], v[196:199], v[8:11]
	v_mfma_f32_16x16x32_bf16 v[4:7], v[164:167], v[204:207], v[4:7]
	v_mfma_f32_16x16x32_bf16 v[0:3], v[172:175], v[204:207], v[0:3]
	s_barrier
	s_add_i32 s65, 0, 0x18000
	s_add_i32 s66, 0, 0x1c000
	v_add_u32_e32 v156, s65, v140
	v_add_u32_e32 v172, s66, v140
	ds_read_b128 v[144:147], v156
	ds_read_b128 v[148:151], v156 offset:1024
	ds_read_b128 v[152:155], v156 offset:2048
	ds_read_b128 v[156:159], v156 offset:3072
	ds_read_b128 v[160:163], v172
	ds_read_b128 v[164:167], v172 offset:1024
	ds_read_b128 v[168:171], v172 offset:2048
	ds_read_b128 v[172:175], v172 offset:3072
	s_add_u32 s40, s40, 0x40000
	s_addc_u32 s41, s41, 0
	s_mov_b32 m0, s51
	v_lshl_add_u64 v[216:217], s[40:41], 0, v[134:135]
	ds_read_b128 v[176:179], v143 offset:32768
	ds_read_b128 v[180:183], v143 offset:33792
	ds_read_b128 v[184:187], v143 offset:34816
	ds_read_b128 v[188:191], v143 offset:35840
	ds_read_b128 v[192:195], v143 offset:36864
	ds_read_b128 v[196:199], v143 offset:37888
	ds_read_b128 v[200:203], v143 offset:38912
	ds_read_b128 v[204:207], v143 offset:39936
	global_load_lds_dwordx4 v[216:217], off
	v_lshl_add_u64 v[216:217], s[40:41], 0, v[130:131]
	s_mov_b32 m0, s52
	s_nop 0
	global_load_lds_dwordx4 v[216:217], off
	s_waitcnt vmcnt(8)
	s_waitcnt lgkmcnt(0)
	s_barrier
; #define PG8_STAGE(bufoff, gbase, voff) do { _Pragma("unroll") for (int _i = 0; _i < 2; ++_i) \
;         __builtin_amdgcn_global_load_lds((const unsigned*)((const char*)(gbase) + (voff)[_i]), (LAS unsigned*)(lds + (bufoff) + ldsw + _i * 8192), 16, 0, 0); } while (0)
; #define PG8_LDA(dst, b, h) do { _Pragma("unroll") for (int m = 0; m < 4; ++m) _Pragma("unroll") for (int k = 0; k < 2; ++k) dst[m][k] = *(const LAS bf16x8*)(lds + PG8_SA(b, h) + aoff + m * 2048 + k * 1024); } while (0)
; #define PG8_MMA(ai, bj, At, Bt) do { __builtin_amdgcn_s_setprio(1); _Pragma("unroll") for (int m = 0; m < 4; ++m) _Pragma("unroll") for (int n = 0; n < 2; ++n) _Pragma("unroll") for (int k = 0; k < 2; ++k) \
;         acc[ai][bj][m][n] = __builtin_amdgcn_mfma_f32_16x16x32_bf16(Bt[n][k], At[m][k], acc[ai][bj][m][n], 0, 0, 0); __builtin_amdgcn_s_setprio(0); } while (0)
; #define PG8_WAIT_V(n) asm volatile("s_waitcnt vmcnt(" #n ")" ::: "memory")
; #define PG8_WAIT_L(n) asm volatile("s_waitcnt lgkmcnt(" #n ")" ::: "memory")
; #define PG8_BAR __builtin_amdgcn_s_barrier()
; #define PG8_SCHED __builtin_amdgcn_sched_barrier(0)
; template <class Epi, class Sched>
; __device__ __forceinline__ void gemm_phase(LAS unsigned char* lds, const GemmP g, const Sched& S, const Epi& E, int tid) {
;     ...
;             PG8_WAIT_V(8); PG8_WAIT_L(0); PG8_BAR; PG8_MMA(0, 0, At, B0); PG8_MMA(0, 1, At, B1); PG8_BAR; PG8_SCHED;
;             PG8_LDA(At, 1, 1); PG8_STAGE(PG8_SB(1, 0), b3, voffB); PG8_STAGE(PG8_SB(1, 1), b3 + hstepB, voffB); PG8_STAGE(PG8_SA(1, 0), a3, voffA);
;             PG8_WAIT_V(8); PG8_WAIT_L(0); PG8_BAR; PG8_MMA(1, 0, At, B0); PG8_MMA(1, 1, At, B1); PG8_BAR; PG8_SCHED;
;         }
;         if (wr == 0) PG8_BAR;
	s_waitcnt lgkmcnt(0)
	v_mfma_f32_16x16x32_bf16 v[124:127], v[144:147], v[176:179], v[124:127]
	v_mfma_f32_16x16x32_bf16 v[120:123], v[152:155], v[176:179], v[120:123]
	v_mfma_f32_16x16x32_bf16 v[116:119], v[144:147], v[184:187], v[116:119]
	v_mfma_f32_16x16x32_bf16 v[112:115], v[152:155], v[184:187], v[112:115]
	v_mfma_f32_16x16x32_bf16 v[100:103], v[144:147], v[192:195], v[100:103]
	v_mfma_f32_16x16x32_bf16 v[96:99], v[152:155], v[192:195], v[96:99]
	v_mfma_f32_16x16x32_bf16 v[84:87], v[144:147], v[200:203], v[84:87]
	v_mfma_f32_16x16x32_bf16 v[80:83], v[152:155], v[200:203], v[80:83]
	v_mfma_f32_16x16x32_bf16 v[124:127], v[148:151], v[180:183], v[124:127]
	v_mfma_f32_16x16x32_bf16 v[120:123], v[156:159], v[180:183], v[120:123]
	v_mfma_f32_16x16x32_bf16 v[116:119], v[148:151], v[188:191], v[116:119]
	v_mfma_f32_16x16x32_bf16 v[112:115], v[156:159], v[188:191], v[112:115]
	v_mfma_f32_16x16x32_bf16 v[100:103], v[148:151], v[196:199], v[100:103]
	v_mfma_f32_16x16x32_bf16 v[96:99], v[156:159], v[196:199], v[96:99]
	v_mfma_f32_16x16x32_bf16 v[84:87], v[148:151], v[204:207], v[84:87]
	v_mfma_f32_16x16x32_bf16 v[80:83], v[156:159], v[204:207], v[80:83]
	v_mfma_f32_16x16x32_bf16 v[108:111], v[160:163], v[176:179], v[108:111]
	v_mfma_f32_16x16x32_bf16 v[104:107], v[168:171], v[176:179], v[104:107]
	v_mfma_f32_16x16x32_bf16 v[92:95], v[160:163], v[184:187], v[92:95]
	v_mfma_f32_16x16x32_bf16 v[88:91], v[168:171], v[184:187], v[88:91]
	v_mfma_f32_16x16x32_bf16 v[76:79], v[160:163], v[192:195], v[76:79]
	v_mfma_f32_16x16x32_bf16 v[72:75], v[168:171], v[192:195], v[72:75]
	v_mfma_f32_16x16x32_bf16 v[68:71], v[160:163], v[200:203], v[68:71]
	v_mfma_f32_16x16x32_bf16 v[64:67], v[168:171], v[200:203], v[64:67]
	v_mfma_f32_16x16x32_bf16 v[108:111], v[164:167], v[180:183], v[108:111]
	v_mfma_f32_16x16x32_bf16 v[104:107], v[172:175], v[180:183], v[104:107]
	v_mfma_f32_16x16x32_bf16 v[92:95], v[164:167], v[188:191], v[92:95]
	v_mfma_f32_16x16x32_bf16 v[88:91], v[172:175], v[188:191], v[88:91]
	v_mfma_f32_16x16x32_bf16 v[76:79], v[164:167], v[196:199], v[76:79]
	v_mfma_f32_16x16x32_bf16 v[72:75], v[172:175], v[196:199], v[72:75]
	v_mfma_f32_16x16x32_bf16 v[68:71], v[164:167], v[204:207], v[68:71]
	v_mfma_f32_16x16x32_bf16 v[64:67], v[172:175], v[204:207], v[64:67]
	s_barrier
	s_add_i32 s40, s65, s48
	v_lshl_add_u64 v[208:209], v[208:209], 0, s[10:11]
	s_mov_b32 m0, s40
	ds_read_b128 v[176:179], v143 offset:49152
	ds_read_b128 v[180:183], v143 offset:50176
	ds_read_b128 v[184:187], v143 offset:51200
	ds_read_b128 v[188:191], v143 offset:52224
	ds_read_b128 v[192:195], v143 offset:53248
	ds_read_b128 v[196:199], v143 offset:54272
	ds_read_b128 v[200:203], v143 offset:55296
	ds_read_b128 v[204:207], v143 offset:56320
	global_load_lds_dwordx4 v[208:209], off
	s_add_i32 m0, s40, 0x2000
	s_add_u32 s38, s38, 0x40080
	v_lshl_add_u64 v[208:209], v[210:211], 0, s[10:11]
	s_addc_u32 s39, s39, 0
	s_add_i32 s40, s66, s48
	global_load_lds_dwordx4 v[208:209], off
	v_lshl_add_u64 v[208:209], s[38:39], 0, v[132:133]
	s_mov_b32 m0, s40
	s_nop 0
	global_load_lds_dwordx4 v[208:209], off
	v_lshl_add_u64 v[208:209], s[38:39], 0, v[128:129]
	s_add_i32 m0, s40, 0x2000
	s_nop 0
	global_load_lds_dwordx4 v[208:209], off
	v_lshl_add_u64 v[208:209], v[212:213], 0, s[10:11]
	s_mov_b32 m0, s54
	s_nop 0
	global_load_lds_dwordx4 v[208:209], off
	v_lshl_add_u64 v[208:209], v[214:215], 0, s[10:11]
	s_mov_b32 m0, s55
	s_nop 0
	global_load_lds_dwordx4 v[208:209], off
	s_waitcnt vmcnt(8)
	s_waitcnt lgkmcnt(0)
	s_barrier
	s_waitcnt lgkmcnt(0)
	v_mfma_f32_16x16x32_bf16 v[60:63], v[144:147], v[176:179], v[60:63]
	v_mfma_f32_16x16x32_bf16 v[56:59], v[152:155], v[176:179], v[56:59]
	v_mfma_f32_16x16x32_bf16 v[52:55], v[144:147], v[184:187], v[52:55]
	v_mfma_f32_16x16x32_bf16 v[48:51], v[152:155], v[184:187], v[48:51]
	v_mfma_f32_16x16x32_bf16 v[36:39], v[144:147], v[192:195], v[36:39]
	v_mfma_f32_16x16x32_bf16 v[32:35], v[152:155], v[192:195], v[32:35]
	v_mfma_f32_16x16x32_bf16 v[20:23], v[144:147], v[200:203], v[20:23]
	v_mfma_f32_16x16x32_bf16 v[16:19], v[152:155], v[200:203], v[16:19]
	v_mfma_f32_16x16x32_bf16 v[60:63], v[148:151], v[180:183], v[60:63]
	v_mfma_f32_16x16x32_bf16 v[56:59], v[156:159], v[180:183], v[56:59]
	v_mfma_f32_16x16x32_bf16 v[52:55], v[148:151], v[188:191], v[52:55]
	v_mfma_f32_16x16x32_bf16 v[48:51], v[156:159], v[188:191], v[48:51]
	v_mfma_f32_16x16x32_bf16 v[36:39], v[148:151], v[196:199], v[36:39]
	v_mfma_f32_16x16x32_bf16 v[32:35], v[156:159], v[196:199], v[32:35]
	v_mfma_f32_16x16x32_bf16 v[20:23], v[148:151], v[204:207], v[20:23]
	v_mfma_f32_16x16x32_bf16 v[16:19], v[156:159], v[204:207], v[16:19]
	v_mfma_f32_16x16x32_bf16 v[44:47], v[160:163], v[176:179], v[44:47]
	v_mfma_f32_16x16x32_bf16 v[40:43], v[168:171], v[176:179], v[40:43]
	v_mfma_f32_16x16x32_bf16 v[28:31], v[160:163], v[184:187], v[28:31]
	v_mfma_f32_16x16x32_bf16 v[24:27], v[168:171], v[184:187], v[24:27]
	v_mfma_f32_16x16x32_bf16 v[12:15], v[160:163], v[192:195], v[12:15]
	v_mfma_f32_16x16x32_bf16 v[8:11], v[168:171], v[192:195], v[8:11]
	v_mfma_f32_16x16x32_bf16 v[4:7], v[160:163], v[200:203], v[4:7]
	v_mfma_f32_16x16x32_bf16 v[0:3], v[168:171], v[200:203], v[0:3]
	v_mfma_f32_16x16x32_bf16 v[44:47], v[164:167], v[180:183], v[44:47]
	v_mfma_f32_16x16x32_bf16 v[40:43], v[172:175], v[180:183], v[40:43]
	v_mfma_f32_16x16x32_bf16 v[28:31], v[164:167], v[188:191], v[28:31]
	v_mfma_f32_16x16x32_bf16 v[24:27], v[172:175], v[188:191], v[24:27]
	v_mfma_f32_16x16x32_bf16 v[12:15], v[164:167], v[196:199], v[12:15]
	v_mfma_f32_16x16x32_bf16 v[8:11], v[172:175], v[196:199], v[8:11]
	v_mfma_f32_16x16x32_bf16 v[4:7], v[164:167], v[204:207], v[4:7]
	v_mfma_f32_16x16x32_bf16 v[0:3], v[172:175], v[204:207], v[0:3]
	s_barrier
	s_add_i32 s64, s64, 2
	s_add_u32 s62, s62, 0x100
	s_addc_u32 s63, s63, 0
	s_add_u32 s36, s36, 0x100
	s_addc_u32 s37, s37, 0
	s_cmp_gt_u32 s64, 13
	s_cbranch_scc0 .LBB0_243
	s_setprio 0
	s_and_b64 vcc, exec, s[12:13]
	s_cbranch_vccz .LBB0_246
	s_barrier

; #define PG8_STAGE(bufoff, gbase, voff) do { _Pragma("unroll") for (int _i = 0; _i < 2; ++_i) \
;         __builtin_amdgcn_global_load_lds((const unsigned*)((const char*)(gbase) + (voff)[_i]), (LAS unsigned*)(lds + (bufoff) + ldsw + _i * 8192), 16, 0, 0); } while (0)
; #define PG8_LDA(dst, b, h) do { _Pragma("unroll") for (int m = 0; m < 4; ++m) _Pragma("unroll") for (int k = 0; k < 2; ++k) dst[m][k] = *(const LAS bf16x8*)(lds + PG8_SA(b, h) + aoff + m * 2048 + k * 1024); } while (0)
; #define PG8_LDB(dst, b, h) do { _Pragma("unroll") for (int n = 0; n < 2; ++n) _Pragma("unroll") for (int k = 0; k < 2; ++k) dst[n][k] = *(const LAS bf16x8*)(lds + PG8_SB(b, h) + boff + n * 2048 + k * 1024); } while (0)
; #define PG8_SCHED __builtin_amdgcn_sched_barrier(0)
; template <class Epi, class Sched>
; __device__ __forceinline__ void gemm_phase(LAS unsigned char* lds, const GemmP g, const Sched& S, const Epi& E, int tid) {
;     ...
;         for (int t = 0; t < nt; t += 2) {
;             const bool last = (t == nt - 2);
;             const char* a1 = cA + (size_t)(t + 1) * kstep;
;             const char* a2 = last ? nA : cA + (size_t)(t + 2) * kstep; const char* b2 = last ? nB : cB + (size_t)(t + 2) * kstep;
;             const char* a3 = a2 + kstep; const char* b3 = b2 + kstep;
;             PG8_LDB(B0, 0, 0); PG8_LDB(B1, 0, 1); PG8_SCHED; PG8_LDA(At, 0, 0); PG8_STAGE(PG8_SA(1, 1), a1 + hstepA, voffA);
;     ...
; #pragma unroll
;         for (int a = 0; a < 2; ++a)
; #pragma unroll
;             for (int b = 0; b < 2; ++b)
; #pragma unroll
;                 for (int m = 0; m < 4; ++m)
; #pragma unroll
;                     for (int n = 0; n < 2; ++n) acc[a][b][m][n] = (f32x4){0.f, 0.f, 0.f, 0.f};
;         cur = nxt; cA = nA; cB = nB; ++ui;
.LBB0_995:
	s_add_u32 s5, s28, 0x100
	s_addc_u32 s56, s29, 0
	s_add_u32 s26, s26, 0x40080
	v_mov_b32_e32 v0, 0
	s_addc_u32 s27, s27, 0
	s_mov_b32 s57, -2
	v_mov_b32_e32 v1, v0
	v_mov_b32_e32 v2, v0
	v_mov_b32_e32 v3, v0
	v_mov_b32_e32 v4, v0
	v_mov_b32_e32 v5, v0
	v_mov_b32_e32 v6, v0
	v_mov_b32_e32 v7, v0
	v_mov_b32_e32 v16, v0
	v_mov_b32_e32 v17, v0
	v_mov_b32_e32 v18, v0
	v_mov_b32_e32 v19, v0
	v_mov_b32_e32 v20, v0
	v_mov_b32_e32 v21, v0
	v_mov_b32_e32 v22, v0
	v_mov_b32_e32 v23, v0
	v_mov_b32_e32 v32, v0
	v_mov_b32_e32 v33, v0
	v_mov_b32_e32 v34, v0
	v_mov_b32_e32 v35, v0
	v_mov_b32_e32 v36, v0
	v_mov_b32_e32 v37, v0
	v_mov_b32_e32 v38, v0
	v_mov_b32_e32 v39, v0
	v_mov_b32_e32 v48, v0
	v_mov_b32_e32 v49, v0
	v_mov_b32_e32 v50, v0
	v_mov_b32_e32 v51, v0
	v_mov_b32_e32 v52, v0
	v_mov_b32_e32 v53, v0
	v_mov_b32_e32 v54, v0
	v_mov_b32_e32 v55, v0
	v_mov_b32_e32 v8, v0
	v_mov_b32_e32 v9, v0
	v_mov_b32_e32 v10, v0
	v_mov_b32_e32 v11, v0
	v_mov_b32_e32 v12, v0
	v_mov_b32_e32 v13, v0
	v_mov_b32_e32 v14, v0
	v_mov_b32_e32 v15, v0
	v_mov_b32_e32 v24, v0
	v_mov_b32_e32 v25, v0
	v_mov_b32_e32 v26, v0
	v_mov_b32_e32 v27, v0
	v_mov_b32_e32 v28, v0
	v_mov_b32_e32 v29, v0
	v_mov_b32_e32 v30, v0
	v_mov_b32_e32 v31, v0
	v_mov_b32_e32 v40, v0
	v_mov_b32_e32 v41, v0
	v_mov_b32_e32 v42, v0
	v_mov_b32_e32 v43, v0
	v_mov_b32_e32 v44, v0
	v_mov_b32_e32 v45, v0
	v_mov_b32_e32 v46, v0
	v_mov_b32_e32 v47, v0
	v_mov_b32_e32 v56, v0
	v_mov_b32_e32 v57, v0
	v_mov_b32_e32 v58, v0
	v_mov_b32_e32 v59, v0
	v_mov_b32_e32 v60, v0
	v_mov_b32_e32 v61, v0
	v_mov_b32_e32 v62, v0
	v_mov_b32_e32 v63, v0
	v_mov_b32_e32 v64, v0
	v_mov_b32_e32 v65, v0
	v_mov_b32_e32 v66, v0
	v_mov_b32_e32 v67, v0
	v_mov_b32_e32 v68, v0
	v_mov_b32_e32 v69, v0
	v_mov_b32_e32 v70, v0
	v_mov_b32_e32 v71, v0
	v_mov_b32_e32 v80, v0
	v_mov_b32_e32 v81, v0
	v_mov_b32_e32 v82, v0
	v_mov_b32_e32 v83, v0
	v_mov_b32_e32 v84, v0
	v_mov_b32_e32 v85, v0
	v_mov_b32_e32 v86, v0
	v_mov_b32_e32 v87, v0
	v_mov_b32_e32 v96, v0
	v_mov_b32_e32 v97, v0
	v_mov_b32_e32 v98, v0
	v_mov_b32_e32 v99, v0
	v_mov_b32_e32 v100, v0
	v_mov_b32_e32 v101, v0
	v_mov_b32_e32 v102, v0
	v_mov_b32_e32 v103, v0
	v_mov_b32_e32 v112, v0
	v_mov_b32_e32 v113, v0
	v_mov_b32_e32 v114, v0
	v_mov_b32_e32 v115, v0
	v_mov_b32_e32 v116, v0
	v_mov_b32_e32 v117, v0
	v_mov_b32_e32 v118, v0
	v_mov_b32_e32 v119, v0
	v_mov_b32_e32 v72, v0
	v_mov_b32_e32 v73, v0
	v_mov_b32_e32 v74, v0
	v_mov_b32_e32 v75, v0
	v_mov_b32_e32 v76, v0
	v_mov_b32_e32 v77, v0
	v_mov_b32_e32 v78, v0
	v_mov_b32_e32 v79, v0
	v_mov_b32_e32 v88, v0
	v_mov_b32_e32 v89, v0
	v_mov_b32_e32 v90, v0
	v_mov_b32_e32 v91, v0
	v_mov_b32_e32 v92, v0
	v_mov_b32_e32 v93, v0
	v_mov_b32_e32 v94, v0
	v_mov_b32_e32 v95, v0
	v_mov_b32_e32 v104, v0
	v_mov_b32_e32 v105, v0
	v_mov_b32_e32 v106, v0
	v_mov_b32_e32 v107, v0
	v_mov_b32_e32 v108, v0
	v_mov_b32_e32 v109, v0
	v_mov_b32_e32 v110, v0
	v_mov_b32_e32 v111, v0
	v_mov_b32_e32 v120, v0
	v_mov_b32_e32 v121, v0
	v_mov_b32_e32 v122, v0
	v_mov_b32_e32 v123, v0
	v_mov_b32_e32 v124, v0
	v_mov_b32_e32 v125, v0
	v_mov_b32_e32 v126, v0
	v_mov_b32_e32 v127, v0
	s_sub_i32 s32, s44, s4
	s_bfe_u32 s98, s32, 0x10006
	s_bfe_u32 s32, s32, 0x10007
	s_cmp_lg_u64 s[10:11], 0
	s_cselect_b32 s99, 1, 0
	s_xor_b32 s98, s98, s99
	s_or_b32 s99, s98, s32
	s_xor_b32 s32, s32, 1
	s_or_b32 s98, s98, s32
	s_cmp_eq_u32 s43, 0x7fffffff
	s_cselect_b32 s32, 0, s99
	s_cselect_b32 s98, 0, s98
	s_and_b32 s99, s32, s98
.LBB0_996:
	s_add_u32 s28, s26, 0xfffc0080
	s_addc_u32 s29, s27, -1
	s_add_i32 s60, 0, 0x10000
	s_cmp_eq_u32 s57, 12
	s_cselect_b32 s31, s23, s29
	s_cselect_b32 s30, s22, s28
	s_cselect_b32 s29, s25, s56
	s_cselect_b32 s28, s24, s5
	s_add_i32 s62, 0, 0x14000
	v_add_u32_e32 v152, s60, v166
	v_add_u32_e32 v164, s62, v166
	s_cmp_lg_u32 s99, 0
	s_cbranch_scc1 .Lskr_cs_1
	ds_read_b128 v[140:143], v152
	ds_read_b128 v[144:147], v152 offset:1024
	ds_read_b128 v[148:151], v152 offset:2048
	ds_read_b128 v[152:155], v152 offset:3072
	ds_read_b128 v[156:159], v164
	ds_read_b128 v[160:163], v164 offset:1024
	ds_read_b128 v[168:171], v164 offset:2048
	ds_read_b128 v[172:175], v164 offset:3072

; #define PG8_STAGE(bufoff, gbase, voff) do { _Pragma("unroll") for (int _i = 0; _i < 2; ++_i) \
;         __builtin_amdgcn_global_load_lds((const unsigned*)((const char*)(gbase) + (voff)[_i]), (LAS unsigned*)(lds + (bufoff) + ldsw + _i * 8192), 16, 0, 0); } while (0)
; #define PG8_LDA(dst, b, h) do { _Pragma("unroll") for (int m = 0; m < 4; ++m) _Pragma("unroll") for (int k = 0; k < 2; ++k) dst[m][k] = *(const LAS bf16x8*)(lds + PG8_SA(b, h) + aoff + m * 2048 + k * 1024); } while (0)
; #define PG8_LDB(dst, b, h) do { _Pragma("unroll") for (int n = 0; n < 2; ++n) _Pragma("unroll") for (int k = 0; k < 2; ++k) dst[n][k] = *(const LAS bf16x8*)(lds + PG8_SB(b, h) + boff + n * 2048 + k * 1024); } while (0)
; #define PG8_MMA(ai, bj, At, Bt) do { __builtin_amdgcn_s_setprio(1); _Pragma("unroll") for (int m = 0; m < 4; ++m) _Pragma("unroll") for (int n = 0; n < 2; ++n) _Pragma("unroll") for (int k = 0; k < 2; ++k) \
;         acc[ai][bj][m][n] = __builtin_amdgcn_mfma_f32_16x16x32_bf16(Bt[n][k], At[m][k], acc[ai][bj][m][n], 0, 0, 0); __builtin_amdgcn_s_setprio(0); } while (0)
; #define PG8_WAIT_V(n) asm volatile("s_waitcnt vmcnt(" #n ")" ::: "memory")
; #define PG8_WAIT_L(n) asm volatile("s_waitcnt lgkmcnt(" #n ")" ::: "memory")
; #define PG8_BAR __builtin_amdgcn_s_barrier()
; template <class Epi, class Sched>
; __device__ __forceinline__ void gemm_phase(LAS unsigned char* lds, const GemmP g, const Sched& S, const Epi& E, int tid) {
;     ...
;         for (int t = 0; t < nt; t += 2) {
;             const bool last = (t == nt - 2);
;             const char* a1 = cA + (size_t)(t + 1) * kstep;
;             const char* a2 = last ? nA : cA + (size_t)(t + 2) * kstep; const char* b2 = last ? nB : cB + (size_t)(t + 2) * kstep;
;             const char* a3 = a2 + kstep; const char* b3 = b2 + kstep;
;             PG8_LDB(B0, 0, 0); PG8_LDB(B1, 0, 1); PG8_SCHED; PG8_LDA(At, 0, 0); PG8_STAGE(PG8_SA(1, 1), a1 + hstepA, voffA);
;             PG8_WAIT_V(8); PG8_WAIT_L(0); PG8_BAR; PG8_MMA(0, 0, At, B0); PG8_MMA(0, 1, At, B1); PG8_BAR; PG8_SCHED;
;     ...
; #pragma unroll
;         for (int a = 0; a < 2; ++a)
; #pragma unroll
;             for (int b = 0; b < 2; ++b)
; #pragma unroll
;                 for (int m = 0; m < 4; ++m)
; #pragma unroll
;                     for (int n = 0; n < 2; ++n) acc[a][b][m][n] = (f32x4){0.f, 0.f, 0.f, 0.f};
;         cur = nxt; cA = nA; cB = nB; ++ui;
.LBB0_1052:
	s_add_u32 s52, s22, 0x100
	s_addc_u32 s53, s23, 0
	s_add_u32 s20, s20, 0x40080
	v_mov_b32_e32 v0, 0
	s_addc_u32 s21, s21, 0
	s_mov_b32 s54, -2
	v_mov_b32_e32 v1, v0
	v_mov_b32_e32 v2, v0
	v_mov_b32_e32 v3, v0
	v_mov_b32_e32 v4, v0
	v_mov_b32_e32 v5, v0
	v_mov_b32_e32 v6, v0
	v_mov_b32_e32 v7, v0
	v_mov_b32_e32 v8, v0
	v_mov_b32_e32 v9, v0
	v_mov_b32_e32 v10, v0
	v_mov_b32_e32 v11, v0
	v_mov_b32_e32 v12, v0
	v_mov_b32_e32 v13, v0
	v_mov_b32_e32 v14, v0
	v_mov_b32_e32 v15, v0
	v_mov_b32_e32 v24, v0
	v_mov_b32_e32 v25, v0
	v_mov_b32_e32 v26, v0
	v_mov_b32_e32 v27, v0
	v_mov_b32_e32 v28, v0
	v_mov_b32_e32 v29, v0
	v_mov_b32_e32 v30, v0
	v_mov_b32_e32 v31, v0
	v_mov_b32_e32 v40, v0
	v_mov_b32_e32 v41, v0
	v_mov_b32_e32 v42, v0
	v_mov_b32_e32 v43, v0
	v_mov_b32_e32 v44, v0
	v_mov_b32_e32 v45, v0
	v_mov_b32_e32 v46, v0
	v_mov_b32_e32 v47, v0
	v_mov_b32_e32 v16, v0
	v_mov_b32_e32 v17, v0
	v_mov_b32_e32 v18, v0
	v_mov_b32_e32 v19, v0
	v_mov_b32_e32 v20, v0
	v_mov_b32_e32 v21, v0
	v_mov_b32_e32 v22, v0
	v_mov_b32_e32 v23, v0
	v_mov_b32_e32 v32, v0
	v_mov_b32_e32 v33, v0
	v_mov_b32_e32 v34, v0
	v_mov_b32_e32 v35, v0
	v_mov_b32_e32 v36, v0
	v_mov_b32_e32 v37, v0
	v_mov_b32_e32 v38, v0
	v_mov_b32_e32 v39, v0
	v_mov_b32_e32 v48, v0
	v_mov_b32_e32 v49, v0
	v_mov_b32_e32 v50, v0
	v_mov_b32_e32 v51, v0
	v_mov_b32_e32 v52, v0
	v_mov_b32_e32 v53, v0
	v_mov_b32_e32 v54, v0
	v_mov_b32_e32 v55, v0
	v_mov_b32_e32 v56, v0
	v_mov_b32_e32 v57, v0
	v_mov_b32_e32 v58, v0
	v_mov_b32_e32 v59, v0
	v_mov_b32_e32 v60, v0
	v_mov_b32_e32 v61, v0
	v_mov_b32_e32 v62, v0
	v_mov_b32_e32 v63, v0
	v_mov_b32_e32 v64, v0
	v_mov_b32_e32 v65, v0
	v_mov_b32_e32 v66, v0
	v_mov_b32_e32 v67, v0
	v_mov_b32_e32 v68, v0
	v_mov_b32_e32 v69, v0
	v_mov_b32_e32 v70, v0
	v_mov_b32_e32 v71, v0
	v_mov_b32_e32 v72, v0
	v_mov_b32_e32 v73, v0
	v_mov_b32_e32 v74, v0
	v_mov_b32_e32 v75, v0
	v_mov_b32_e32 v76, v0
	v_mov_b32_e32 v77, v0
	v_mov_b32_e32 v78, v0
	v_mov_b32_e32 v79, v0
	v_mov_b32_e32 v88, v0
	v_mov_b32_e32 v89, v0
	v_mov_b32_e32 v90, v0
	v_mov_b32_e32 v91, v0
	v_mov_b32_e32 v92, v0
	v_mov_b32_e32 v93, v0
	v_mov_b32_e32 v94, v0
	v_mov_b32_e32 v95, v0
	v_mov_b32_e32 v104, v0
	v_mov_b32_e32 v105, v0
	v_mov_b32_e32 v106, v0
	v_mov_b32_e32 v107, v0
	v_mov_b32_e32 v108, v0
	v_mov_b32_e32 v109, v0
	v_mov_b32_e32 v110, v0
	v_mov_b32_e32 v111, v0
	v_mov_b32_e32 v80, v0
	v_mov_b32_e32 v81, v0
	v_mov_b32_e32 v82, v0
	v_mov_b32_e32 v83, v0
	v_mov_b32_e32 v84, v0
	v_mov_b32_e32 v85, v0
	v_mov_b32_e32 v86, v0
	v_mov_b32_e32 v87, v0
	v_mov_b32_e32 v96, v0
	v_mov_b32_e32 v97, v0
	v_mov_b32_e32 v98, v0
	v_mov_b32_e32 v99, v0
	v_mov_b32_e32 v100, v0
	v_mov_b32_e32 v101, v0
	v_mov_b32_e32 v102, v0
	v_mov_b32_e32 v103, v0
	v_mov_b32_e32 v112, v0
	v_mov_b32_e32 v113, v0
	v_mov_b32_e32 v114, v0
	v_mov_b32_e32 v115, v0
	v_mov_b32_e32 v116, v0
	v_mov_b32_e32 v117, v0
	v_mov_b32_e32 v118, v0
	v_mov_b32_e32 v119, v0
	v_mov_b32_e32 v120, v0
	v_mov_b32_e32 v121, v0
	v_mov_b32_e32 v122, v0
	v_mov_b32_e32 v123, v0
	v_mov_b32_e32 v124, v0
	v_mov_b32_e32 v125, v0
	v_mov_b32_e32 v126, v0
	v_mov_b32_e32 v127, v0
.LBB0_1053:
	s_add_u32 s22, s20, 0xfffc0080
	s_addc_u32 s23, s21, -1
	s_add_i32 s56, 0, 0x10000
	s_cmp_eq_u32 s54, 12
	s_cselect_b32 s25, s17, s23
	s_cselect_b32 s24, s16, s22
	v_add_u32_e32 v141, s56, v139
	s_cselect_b32 s23, s19, s53
	s_cselect_b32 s22, s18, s52
	s_add_i32 s58, 0, 0x14000
	ds_read_b128 v[142:145], v141
	ds_read_b128 v[146:149], v141 offset:1024
	ds_read_b128 v[150:153], v141 offset:2048
	ds_read_b128 v[154:157], v141 offset:3072
	v_add_u32_e32 v141, s58, v139
	ds_read_b128 v[158:161], v141
	ds_read_b128 v[162:165], v141 offset:1024
	ds_read_b128 v[166:169], v141 offset:2048
	ds_read_b128 v[170:173], v141 offset:3072
	v_lshl_add_u64 v[194:195], s[20:21], 0, v[136:137]
	s_add_i32 m0, s39, 0xc000
	ds_read_b128 v[174:177], v140
	ds_read_b128 v[178:181], v140 offset:1024
	ds_read_b128 v[182:185], v140 offset:2048
	ds_read_b128 v[186:189], v140 offset:3072
	ds_read_b128 v[190:193], v140 offset:4096
	ds_read_b128 v[206:209], v140 offset:5120
	ds_read_b128 v[210:213], v140 offset:6144
	ds_read_b128 v[214:217], v140 offset:7168
	global_load_lds_dwordx4 v[194:195], off
	v_lshl_add_u64 v[194:195], s[20:21], 0, v[134:135]
	s_add_i32 m0, s39, 0xe000
	s_nop 0
	global_load_lds_dwordx4 v[194:195], off
	s_waitcnt vmcnt(8)
	s_waitcnt lgkmcnt(0)
	s_barrier
	s_waitcnt lgkmcnt(0)
	v_mfma_f32_16x16x32_bf16 v[124:127], v[142:145], v[174:177], v[124:127]
	v_mfma_f32_16x16x32_bf16 v[120:123], v[150:153], v[174:177], v[120:123]
	v_mfma_f32_16x16x32_bf16 v[116:119], v[142:145], v[182:185], v[116:119]
	v_mfma_f32_16x16x32_bf16 v[112:115], v[150:153], v[182:185], v[112:115]
	v_mfma_f32_16x16x32_bf16 v[100:103], v[142:145], v[190:193], v[100:103]
	v_mfma_f32_16x16x32_bf16 v[96:99], v[150:153], v[190:193], v[96:99]
	v_mfma_f32_16x16x32_bf16 v[84:87], v[142:145], v[210:213], v[84:87]
	v_mfma_f32_16x16x32_bf16 v[80:83], v[150:153], v[210:213], v[80:83]
	v_mfma_f32_16x16x32_bf16 v[124:127], v[146:149], v[178:181], v[124:127]
	v_mfma_f32_16x16x32_bf16 v[120:123], v[154:157], v[178:181], v[120:123]
	v_mfma_f32_16x16x32_bf16 v[116:119], v[146:149], v[186:189], v[116:119]
	v_mfma_f32_16x16x32_bf16 v[112:115], v[154:157], v[186:189], v[112:115]
	v_mfma_f32_16x16x32_bf16 v[100:103], v[146:149], v[206:209], v[100:103]
	v_mfma_f32_16x16x32_bf16 v[96:99], v[154:157], v[206:209], v[96:99]
	v_mfma_f32_16x16x32_bf16 v[84:87], v[146:149], v[214:217], v[84:87]
	v_mfma_f32_16x16x32_bf16 v[80:83], v[154:157], v[214:217], v[80:83]
	v_mfma_f32_16x16x32_bf16 v[108:111], v[158:161], v[174:177], v[108:111]
	v_mfma_f32_16x16x32_bf16 v[104:107], v[166:169], v[174:177], v[104:107]
	v_mfma_f32_16x16x32_bf16 v[92:95], v[158:161], v[182:185], v[92:95]
	v_mfma_f32_16x16x32_bf16 v[88:91], v[166:169], v[182:185], v[88:91]
	v_mfma_f32_16x16x32_bf16 v[76:79], v[158:161], v[190:193], v[76:79]
	v_mfma_f32_16x16x32_bf16 v[72:75], v[166:169], v[190:193], v[72:75]
	v_mfma_f32_16x16x32_bf16 v[68:71], v[158:161], v[210:213], v[68:71]
	v_mfma_f32_16x16x32_bf16 v[64:67], v[166:169], v[210:213], v[64:67]
	v_mfma_f32_16x16x32_bf16 v[108:111], v[162:165], v[178:181], v[108:111]
	v_mfma_f32_16x16x32_bf16 v[104:107], v[170:173], v[178:181], v[104:107]
	v_mfma_f32_16x16x32_bf16 v[92:95], v[162:165], v[186:189], v[92:95]
	v_mfma_f32_16x16x32_bf16 v[88:91], v[170:173], v[186:189], v[88:91]
	v_mfma_f32_16x16x32_bf16 v[76:79], v[162:165], v[206:209], v[76:79]
	v_mfma_f32_16x16x32_bf16 v[72:75], v[170:173], v[206:209], v[72:75]
	v_mfma_f32_16x16x32_bf16 v[68:71], v[162:165], v[214:217], v[68:71]
	v_mfma_f32_16x16x32_bf16 v[64:67], v[170:173], v[214:217], v[64:67]
	s_barrier
; #define PG8_STAGE(bufoff, gbase, voff) do { _Pragma("unroll") for (int _i = 0; _i < 2; ++_i) \
;         __builtin_amdgcn_global_load_lds((const unsigned*)((const char*)(gbase) + (voff)[_i]), (LAS unsigned*)(lds + (bufoff) + ldsw + _i * 8192), 16, 0, 0); } while (0)
; #define PG8_LDA(dst, b, h) do { _Pragma("unroll") for (int m = 0; m < 4; ++m) _Pragma("unroll") for (int k = 0; k < 2; ++k) dst[m][k] = *(const LAS bf16x8*)(lds + PG8_SA(b, h) + aoff + m * 2048 + k * 1024); } while (0)
; #define PG8_LDB(dst, b, h) do { _Pragma("unroll") for (int n = 0; n < 2; ++n) _Pragma("unroll") for (int k = 0; k < 2; ++k) dst[n][k] = *(const LAS bf16x8*)(lds + PG8_SB(b, h) + boff + n * 2048 + k * 1024); } while (0)
; #define PG8_MMA(ai, bj, At, Bt) do { __builtin_amdgcn_s_setprio(1); _Pragma("unroll") for (int m = 0; m < 4; ++m) _Pragma("unroll") for (int n = 0; n < 2; ++n) _Pragma("unroll") for (int k = 0; k < 2; ++k) \
;         acc[ai][bj][m][n] = __builtin_amdgcn_mfma_f32_16x16x32_bf16(Bt[n][k], At[m][k], acc[ai][bj][m][n], 0, 0, 0); __builtin_amdgcn_s_setprio(0); } while (0)
; #define PG8_WAIT_V(n) asm volatile("s_waitcnt vmcnt(" #n ")" ::: "memory")
; #define PG8_WAIT_L(n) asm volatile("s_waitcnt lgkmcnt(" #n ")" ::: "memory")
; #define PG8_BAR __builtin_amdgcn_s_barrier()
; #define PG8_SCHED __builtin_amdgcn_sched_barrier(0)
; template <class Epi, class Sched>
; __device__ __forceinline__ void gemm_phase(LAS unsigned char* lds, const GemmP g, const Sched& S, const Epi& E, int tid) {
;     ...
;             PG8_LDA(At, 0, 1); PG8_STAGE(PG8_SB(0, 0), b2, voffB); PG8_STAGE(PG8_SB(0, 1), b2 + hstepB, voffB); PG8_STAGE(PG8_SA(0, 0), a2, voffA);
;             PG8_WAIT_V(8); PG8_WAIT_L(0); PG8_BAR; PG8_MMA(1, 0, At, B0); PG8_MMA(1, 1, At, B1); PG8_BAR; PG8_SCHED;
;             PG8_LDB(B0, 1, 0); PG8_LDB(B1, 1, 1); PG8_SCHED; PG8_LDA(At, 1, 0); PG8_STAGE(PG8_SA(0, 1), a2 + hstepA, voffA);
;             PG8_WAIT_V(8); PG8_WAIT_L(0); PG8_BAR; PG8_MMA(0, 0, At, B0); PG8_MMA(0, 1, At, B1); PG8_BAR; PG8_SCHED;
	s_add_i32 s56, s56, s38
	v_lshl_add_u64 v[194:195], s[22:23], 0, v[196:197]
	s_mov_b32 m0, s56
	ds_read_b128 v[174:177], v140 offset:16384
	ds_read_b128 v[178:181], v140 offset:17408
	ds_read_b128 v[182:185], v140 offset:18432
	ds_read_b128 v[186:189], v140 offset:19456
	ds_read_b128 v[190:193], v140 offset:20480
	ds_read_b128 v[206:209], v140 offset:21504
	ds_read_b128 v[210:213], v140 offset:22528
	ds_read_b128 v[214:217], v140 offset:23552
	global_load_lds_dwordx4 v[194:195], off
	s_add_i32 m0, s56, 0x2000
	s_add_u32 s56, s22, 0x40000
	v_lshl_add_u64 v[198:199], s[22:23], 0, v[128:129]
	s_addc_u32 s57, s23, 0
	s_add_i32 s58, s58, s38
	global_load_lds_dwordx4 v[198:199], off
	v_lshl_add_u64 v[200:201], s[56:57], 0, v[196:197]
	s_mov_b32 m0, s58
	v_lshl_add_u64 v[220:221], s[24:25], 0, v[130:131]
	global_load_lds_dwordx4 v[200:201], off
	v_lshl_add_u64 v[200:201], s[56:57], 0, v[128:129]
	s_add_i32 m0, s58, 0x2000
	s_nop 0
	global_load_lds_dwordx4 v[200:201], off
	v_lshl_add_u64 v[200:201], s[24:25], 0, v[132:133]
	s_mov_b32 m0, s39
	s_nop 0
	global_load_lds_dwordx4 v[200:201], off
	s_mov_b32 m0, s40
	s_nop 0
	global_load_lds_dwordx4 v[220:221], off
	s_waitcnt vmcnt(8)
	s_waitcnt lgkmcnt(0)
	s_barrier
	s_waitcnt lgkmcnt(0)
	v_mfma_f32_16x16x32_bf16 v[60:63], v[142:145], v[174:177], v[60:63]
	v_mfma_f32_16x16x32_bf16 v[56:59], v[150:153], v[174:177], v[56:59]
	v_mfma_f32_16x16x32_bf16 v[52:55], v[142:145], v[182:185], v[52:55]
	v_mfma_f32_16x16x32_bf16 v[48:51], v[150:153], v[182:185], v[48:51]
	v_mfma_f32_16x16x32_bf16 v[36:39], v[142:145], v[190:193], v[36:39]
	v_mfma_f32_16x16x32_bf16 v[32:35], v[150:153], v[190:193], v[32:35]
	v_mfma_f32_16x16x32_bf16 v[20:23], v[142:145], v[210:213], v[20:23]
	v_mfma_f32_16x16x32_bf16 v[16:19], v[150:153], v[210:213], v[16:19]
	v_mfma_f32_16x16x32_bf16 v[60:63], v[146:149], v[178:181], v[60:63]
	v_mfma_f32_16x16x32_bf16 v[56:59], v[154:157], v[178:181], v[56:59]
	v_mfma_f32_16x16x32_bf16 v[52:55], v[146:149], v[186:189], v[52:55]
	v_mfma_f32_16x16x32_bf16 v[48:51], v[154:157], v[186:189], v[48:51]
	v_mfma_f32_16x16x32_bf16 v[36:39], v[146:149], v[206:209], v[36:39]
	v_mfma_f32_16x16x32_bf16 v[32:35], v[154:157], v[206:209], v[32:35]
	v_mfma_f32_16x16x32_bf16 v[20:23], v[146:149], v[214:217], v[20:23]
	v_mfma_f32_16x16x32_bf16 v[16:19], v[154:157], v[214:217], v[16:19]
	v_mfma_f32_16x16x32_bf16 v[44:47], v[158:161], v[174:177], v[44:47]
	v_mfma_f32_16x16x32_bf16 v[40:43], v[166:169], v[174:177], v[40:43]
	v_mfma_f32_16x16x32_bf16 v[28:31], v[158:161], v[182:185], v[28:31]
	v_mfma_f32_16x16x32_bf16 v[24:27], v[166:169], v[182:185], v[24:27]
	v_mfma_f32_16x16x32_bf16 v[12:15], v[158:161], v[190:193], v[12:15]
	v_mfma_f32_16x16x32_bf16 v[8:11], v[166:169], v[190:193], v[8:11]
	v_mfma_f32_16x16x32_bf16 v[4:7], v[158:161], v[210:213], v[4:7]
	v_mfma_f32_16x16x32_bf16 v[0:3], v[166:169], v[210:213], v[0:3]
	v_mfma_f32_16x16x32_bf16 v[44:47], v[162:165], v[178:181], v[44:47]
	v_mfma_f32_16x16x32_bf16 v[40:43], v[170:173], v[178:181], v[40:43]
	v_mfma_f32_16x16x32_bf16 v[28:31], v[162:165], v[186:189], v[28:31]
	v_mfma_f32_16x16x32_bf16 v[24:27], v[170:173], v[186:189], v[24:27]
	v_mfma_f32_16x16x32_bf16 v[12:15], v[162:165], v[206:209], v[12:15]
	v_mfma_f32_16x16x32_bf16 v[8:11], v[170:173], v[206:209], v[8:11]
	v_mfma_f32_16x16x32_bf16 v[4:7], v[162:165], v[214:217], v[4:7]
	v_mfma_f32_16x16x32_bf16 v[0:3], v[170:173], v[214:217], v[0:3]
	s_barrier
	s_add_i32 s56, 0, 0x18000
	v_add_u32_e32 v141, s56, v139
	s_add_i32 s57, 0, 0x1c000
	ds_read_b128 v[142:145], v141
	ds_read_b128 v[146:149], v141 offset:1024
	ds_read_b128 v[150:153], v141 offset:2048
	ds_read_b128 v[154:157], v141 offset:3072
	v_add_u32_e32 v141, s57, v139
	ds_read_b128 v[158:161], v141
	ds_read_b128 v[162:165], v141 offset:1024
	ds_read_b128 v[166:169], v141 offset:2048
	ds_read_b128 v[170:173], v141 offset:3072
	s_add_u32 s24, s24, 0x40000
	s_addc_u32 s25, s25, 0
	s_mov_b32 m0, s41
	v_lshl_add_u64 v[222:223], s[24:25], 0, v[132:133]
	ds_read_b128 v[174:177], v140 offset:32768
	ds_read_b128 v[178:181], v140 offset:33792
	ds_read_b128 v[182:185], v140 offset:34816
	ds_read_b128 v[186:189], v140 offset:35840
	ds_read_b128 v[190:193], v140 offset:36864
	ds_read_b128 v[206:209], v140 offset:37888
	ds_read_b128 v[210:213], v140 offset:38912
	ds_read_b128 v[214:217], v140 offset:39936
	global_load_lds_dwordx4 v[222:223], off
	v_lshl_add_u64 v[222:223], s[24:25], 0, v[130:131]
	s_mov_b32 m0, s42
	s_nop 0
	global_load_lds_dwordx4 v[222:223], off
	s_waitcnt vmcnt(8)
	s_waitcnt lgkmcnt(0)
	s_barrier
; #define PG8_STAGE(bufoff, gbase, voff) do { _Pragma("unroll") for (int _i = 0; _i < 2; ++_i) \
;         __builtin_amdgcn_global_load_lds((const unsigned*)((const char*)(gbase) + (voff)[_i]), (LAS unsigned*)(lds + (bufoff) + ldsw + _i * 8192), 16, 0, 0); } while (0)
; #define PG8_LDA(dst, b, h) do { _Pragma("unroll") for (int m = 0; m < 4; ++m) _Pragma("unroll") for (int k = 0; k < 2; ++k) dst[m][k] = *(const LAS bf16x8*)(lds + PG8_SA(b, h) + aoff + m * 2048 + k * 1024); } while (0)
; #define PG8_MMA(ai, bj, At, Bt) do { __builtin_amdgcn_s_setprio(1); _Pragma("unroll") for (int m = 0; m < 4; ++m) _Pragma("unroll") for (int n = 0; n < 2; ++n) _Pragma("unroll") for (int k = 0; k < 2; ++k) \
;         acc[ai][bj][m][n] = __builtin_amdgcn_mfma_f32_16x16x32_bf16(Bt[n][k], At[m][k], acc[ai][bj][m][n], 0, 0, 0); __builtin_amdgcn_s_setprio(0); } while (0)
; #define PG8_WAIT_V(n) asm volatile("s_waitcnt vmcnt(" #n ")" ::: "memory")
; #define PG8_WAIT_L(n) asm volatile("s_waitcnt lgkmcnt(" #n ")" ::: "memory")
; #define PG8_BAR __builtin_amdgcn_s_barrier()
; #define PG8_SCHED __builtin_amdgcn_sched_barrier(0)
; template <class Epi, class Sched>
; __device__ __forceinline__ void gemm_phase(LAS unsigned char* lds, const GemmP g, const Sched& S, const Epi& E, int tid) {
;     ...
;             PG8_WAIT_V(8); PG8_WAIT_L(0); PG8_BAR; PG8_MMA(0, 0, At, B0); PG8_MMA(0, 1, At, B1); PG8_BAR; PG8_SCHED;
;             PG8_LDA(At, 1, 1); PG8_STAGE(PG8_SB(1, 0), b3, voffB); PG8_STAGE(PG8_SB(1, 1), b3 + hstepB, voffB); PG8_STAGE(PG8_SA(1, 0), a3, voffA);
;             PG8_WAIT_V(8); PG8_WAIT_L(0); PG8_BAR; PG8_MMA(1, 0, At, B0); PG8_MMA(1, 1, At, B1); PG8_BAR; PG8_SCHED;
;         }
;         if (wr == 0) PG8_BAR;
	s_waitcnt lgkmcnt(0)
	v_mfma_f32_16x16x32_bf16 v[124:127], v[142:145], v[174:177], v[124:127]
	v_mfma_f32_16x16x32_bf16 v[120:123], v[150:153], v[174:177], v[120:123]
	v_mfma_f32_16x16x32_bf16 v[116:119], v[142:145], v[182:185], v[116:119]
	v_mfma_f32_16x16x32_bf16 v[112:115], v[150:153], v[182:185], v[112:115]
	v_mfma_f32_16x16x32_bf16 v[100:103], v[142:145], v[190:193], v[100:103]
	v_mfma_f32_16x16x32_bf16 v[96:99], v[150:153], v[190:193], v[96:99]
	v_mfma_f32_16x16x32_bf16 v[84:87], v[142:145], v[210:213], v[84:87]
	v_mfma_f32_16x16x32_bf16 v[80:83], v[150:153], v[210:213], v[80:83]
	v_mfma_f32_16x16x32_bf16 v[124:127], v[146:149], v[178:181], v[124:127]
	v_mfma_f32_16x16x32_bf16 v[120:123], v[154:157], v[178:181], v[120:123]
	v_mfma_f32_16x16x32_bf16 v[116:119], v[146:149], v[186:189], v[116:119]
	v_mfma_f32_16x16x32_bf16 v[112:115], v[154:157], v[186:189], v[112:115]
	v_mfma_f32_16x16x32_bf16 v[100:103], v[146:149], v[206:209], v[100:103]
	v_mfma_f32_16x16x32_bf16 v[96:99], v[154:157], v[206:209], v[96:99]
	v_mfma_f32_16x16x32_bf16 v[84:87], v[146:149], v[214:217], v[84:87]
	v_mfma_f32_16x16x32_bf16 v[80:83], v[154:157], v[214:217], v[80:83]
	v_mfma_f32_16x16x32_bf16 v[108:111], v[158:161], v[174:177], v[108:111]
	v_mfma_f32_16x16x32_bf16 v[104:107], v[166:169], v[174:177], v[104:107]
	v_mfma_f32_16x16x32_bf16 v[92:95], v[158:161], v[182:185], v[92:95]
	v_mfma_f32_16x16x32_bf16 v[88:91], v[166:169], v[182:185], v[88:91]
	v_mfma_f32_16x16x32_bf16 v[76:79], v[158:161], v[190:193], v[76:79]
	v_mfma_f32_16x16x32_bf16 v[72:75], v[166:169], v[190:193], v[72:75]
	v_mfma_f32_16x16x32_bf16 v[68:71], v[158:161], v[210:213], v[68:71]
	v_mfma_f32_16x16x32_bf16 v[64:67], v[166:169], v[210:213], v[64:67]
	v_mfma_f32_16x16x32_bf16 v[108:111], v[162:165], v[178:181], v[108:111]
	v_mfma_f32_16x16x32_bf16 v[104:107], v[170:173], v[178:181], v[104:107]
	v_mfma_f32_16x16x32_bf16 v[92:95], v[162:165], v[186:189], v[92:95]
	v_mfma_f32_16x16x32_bf16 v[88:91], v[170:173], v[186:189], v[88:91]
	v_mfma_f32_16x16x32_bf16 v[76:79], v[162:165], v[206:209], v[76:79]
	v_mfma_f32_16x16x32_bf16 v[72:75], v[170:173], v[206:209], v[72:75]
	v_mfma_f32_16x16x32_bf16 v[68:71], v[162:165], v[214:217], v[68:71]
	v_mfma_f32_16x16x32_bf16 v[64:67], v[170:173], v[214:217], v[64:67]
	s_barrier
	s_add_i32 s24, s56, s38
	v_lshl_add_u64 v[194:195], v[194:195], 0, s[80:81]
	s_mov_b32 m0, s24
	ds_read_b128 v[174:177], v140 offset:49152
	ds_read_b128 v[178:181], v140 offset:50176
	ds_read_b128 v[182:185], v140 offset:51200
	ds_read_b128 v[186:189], v140 offset:52224
	ds_read_b128 v[190:193], v140 offset:53248
	ds_read_b128 v[206:209], v140 offset:54272
	ds_read_b128 v[210:213], v140 offset:55296
	ds_read_b128 v[214:217], v140 offset:56320
	global_load_lds_dwordx4 v[194:195], off
	s_add_i32 m0, s24, 0x2000
	s_add_u32 s22, s22, 0x40080
	v_lshl_add_u64 v[194:195], v[198:199], 0, s[80:81]
	s_addc_u32 s23, s23, 0
	s_add_i32 s24, s57, s38
	global_load_lds_dwordx4 v[194:195], off
	v_lshl_add_u64 v[194:195], s[22:23], 0, v[196:197]
	s_mov_b32 m0, s24
	s_nop 0
	global_load_lds_dwordx4 v[194:195], off
	v_lshl_add_u64 v[194:195], s[22:23], 0, v[128:129]
	s_add_i32 m0, s24, 0x2000
	s_nop 0
	global_load_lds_dwordx4 v[194:195], off
	v_lshl_add_u64 v[194:195], v[200:201], 0, s[80:81]
	s_mov_b32 m0, s45
	s_nop 0
	global_load_lds_dwordx4 v[194:195], off
	v_lshl_add_u64 v[194:195], v[220:221], 0, s[80:81]
	s_mov_b32 m0, s46
	s_nop 0
	global_load_lds_dwordx4 v[194:195], off
	s_waitcnt vmcnt(8)
	s_waitcnt lgkmcnt(0)
	s_barrier
	s_waitcnt lgkmcnt(0)
	v_mfma_f32_16x16x32_bf16 v[60:63], v[142:145], v[174:177], v[60:63]
	v_mfma_f32_16x16x32_bf16 v[56:59], v[150:153], v[174:177], v[56:59]
	v_mfma_f32_16x16x32_bf16 v[52:55], v[142:145], v[182:185], v[52:55]
	v_mfma_f32_16x16x32_bf16 v[48:51], v[150:153], v[182:185], v[48:51]
	v_mfma_f32_16x16x32_bf16 v[36:39], v[142:145], v[190:193], v[36:39]
	v_mfma_f32_16x16x32_bf16 v[32:35], v[150:153], v[190:193], v[32:35]
	v_mfma_f32_16x16x32_bf16 v[20:23], v[142:145], v[210:213], v[20:23]
	v_mfma_f32_16x16x32_bf16 v[16:19], v[150:153], v[210:213], v[16:19]
	v_mfma_f32_16x16x32_bf16 v[60:63], v[146:149], v[178:181], v[60:63]
	v_mfma_f32_16x16x32_bf16 v[56:59], v[154:157], v[178:181], v[56:59]
	v_mfma_f32_16x16x32_bf16 v[52:55], v[146:149], v[186:189], v[52:55]
	v_mfma_f32_16x16x32_bf16 v[48:51], v[154:157], v[186:189], v[48:51]
	v_mfma_f32_16x16x32_bf16 v[36:39], v[146:149], v[206:209], v[36:39]
	v_mfma_f32_16x16x32_bf16 v[32:35], v[154:157], v[206:209], v[32:35]
	v_mfma_f32_16x16x32_bf16 v[20:23], v[146:149], v[214:217], v[20:23]
	v_mfma_f32_16x16x32_bf16 v[16:19], v[154:157], v[214:217], v[16:19]
	v_mfma_f32_16x16x32_bf16 v[44:47], v[158:161], v[174:177], v[44:47]
	v_mfma_f32_16x16x32_bf16 v[40:43], v[166:169], v[174:177], v[40:43]
	v_mfma_f32_16x16x32_bf16 v[28:31], v[158:161], v[182:185], v[28:31]
	v_mfma_f32_16x16x32_bf16 v[24:27], v[166:169], v[182:185], v[24:27]
	v_mfma_f32_16x16x32_bf16 v[12:15], v[158:161], v[190:193], v[12:15]
	v_mfma_f32_16x16x32_bf16 v[8:11], v[166:169], v[190:193], v[8:11]
	v_mfma_f32_16x16x32_bf16 v[4:7], v[158:161], v[210:213], v[4:7]
	v_mfma_f32_16x16x32_bf16 v[0:3], v[166:169], v[210:213], v[0:3]
	v_mfma_f32_16x16x32_bf16 v[44:47], v[162:165], v[178:181], v[44:47]
	v_mfma_f32_16x16x32_bf16 v[40:43], v[170:173], v[178:181], v[40:43]
	v_mfma_f32_16x16x32_bf16 v[28:31], v[162:165], v[186:189], v[28:31]
	v_mfma_f32_16x16x32_bf16 v[24:27], v[170:173], v[186:189], v[24:27]
	v_mfma_f32_16x16x32_bf16 v[12:15], v[162:165], v[206:209], v[12:15]
	v_mfma_f32_16x16x32_bf16 v[8:11], v[170:173], v[206:209], v[8:11]
	v_mfma_f32_16x16x32_bf16 v[4:7], v[162:165], v[214:217], v[4:7]
	v_mfma_f32_16x16x32_bf16 v[0:3], v[170:173], v[214:217], v[0:3]
	s_barrier
	s_add_i32 s54, s54, 2
	s_add_u32 s52, s52, 0x100
	s_addc_u32 s53, s53, 0
	s_add_u32 s20, s20, 0x100
	s_addc_u32 s21, s21, 0
	s_cmp_gt_u32 s54, 13
	s_cbranch_scc0 .LBB0_1053
	s_setprio 0
	s_and_b64 vcc, exec, s[12:13]
	s_cbranch_vccz .LBB0_1056
	s_barrier

; #define PG8_STAGE(bufoff, gbase, voff) do { _Pragma("unroll") for (int _i = 0; _i < 2; ++_i) \
;         __builtin_amdgcn_global_load_lds((const unsigned*)((const char*)(gbase) + (voff)[_i]), (LAS unsigned*)(lds + (bufoff) + ldsw + _i * 8192), 16, 0, 0); } while (0)
; #define PG8_LDA(dst, b, h) do { _Pragma("unroll") for (int m = 0; m < 4; ++m) _Pragma("unroll") for (int k = 0; k < 2; ++k) dst[m][k] = *(const LAS bf16x8*)(lds + PG8_SA(b, h) + aoff + m * 2048 + k * 1024); } while (0)
; #define PG8_LDB(dst, b, h) do { _Pragma("unroll") for (int n = 0; n < 2; ++n) _Pragma("unroll") for (int k = 0; k < 2; ++k) dst[n][k] = *(const LAS bf16x8*)(lds + PG8_SB(b, h) + boff + n * 2048 + k * 1024); } while (0)
; #define PG8_MMA(ai, bj, At, Bt) do { __builtin_amdgcn_s_setprio(1); _Pragma("unroll") for (int m = 0; m < 4; ++m) _Pragma("unroll") for (int n = 0; n < 2; ++n) _Pragma("unroll") for (int k = 0; k < 2; ++k) \
;         acc[ai][bj][m][n] = __builtin_amdgcn_mfma_f32_16x16x32_bf16(Bt[n][k], At[m][k], acc[ai][bj][m][n], 0, 0, 0); __builtin_amdgcn_s_setprio(0); } while (0)
; #define PG8_WAIT_V(n) asm volatile("s_waitcnt vmcnt(" #n ")" ::: "memory")
; #define PG8_WAIT_L(n) asm volatile("s_waitcnt lgkmcnt(" #n ")" ::: "memory")
; #define PG8_BAR __builtin_amdgcn_s_barrier()
; template <class Epi, class Sched>
; __device__ __forceinline__ void gemm_phase(LAS unsigned char* lds, const GemmP g, const Sched& S, const Epi& E, int tid) {
;     ...
;         for (int t = 0; t < nt; t += 2) {
;             const bool last = (t == nt - 2);
;             const char* a1 = cA + (size_t)(t + 1) * kstep;
;             const char* a2 = last ? nA : cA + (size_t)(t + 2) * kstep; const char* b2 = last ? nB : cB + (size_t)(t + 2) * kstep;
;             const char* a3 = a2 + kstep; const char* b3 = b2 + kstep;
;             PG8_LDB(B0, 0, 0); PG8_LDB(B1, 0, 1); PG8_SCHED; PG8_LDA(At, 0, 0); PG8_STAGE(PG8_SA(1, 1), a1 + hstepA, voffA);
;             PG8_WAIT_V(8); PG8_WAIT_L(0); PG8_BAR; PG8_MMA(0, 0, At, B0); PG8_MMA(0, 1, At, B1); PG8_BAR; PG8_SCHED;
;     ...
; #pragma unroll
;         for (int a = 0; a < 2; ++a)
; #pragma unroll
;             for (int b = 0; b < 2; ++b)
; #pragma unroll
;                 for (int m = 0; m < 4; ++m)
; #pragma unroll
;                     for (int n = 0; n < 2; ++n) acc[a][b][m][n] = (f32x4){0.f, 0.f, 0.f, 0.f};
;         cur = nxt; cA = nA; cB = nB; ++ui;
.LBB0_1072:
	s_add_u32 s45, s18, 0x100
	s_addc_u32 s46, s19, 0
	s_add_u32 s16, s16, 0x40080
	v_mov_b32_e32 v0, 0
	s_addc_u32 s17, s17, 0
	s_mov_b32 s47, -2
	v_mov_b32_e32 v1, v0
	v_mov_b32_e32 v2, v0
	v_mov_b32_e32 v3, v0
	v_mov_b32_e32 v4, v0
	v_mov_b32_e32 v5, v0
	v_mov_b32_e32 v6, v0
	v_mov_b32_e32 v7, v0
	v_mov_b32_e32 v8, v0
	v_mov_b32_e32 v9, v0
	v_mov_b32_e32 v10, v0
	v_mov_b32_e32 v11, v0
	v_mov_b32_e32 v12, v0
	v_mov_b32_e32 v13, v0
	v_mov_b32_e32 v14, v0
	v_mov_b32_e32 v15, v0
	v_mov_b32_e32 v24, v0
	v_mov_b32_e32 v25, v0
	v_mov_b32_e32 v26, v0
	v_mov_b32_e32 v27, v0
	v_mov_b32_e32 v28, v0
	v_mov_b32_e32 v29, v0
	v_mov_b32_e32 v30, v0
	v_mov_b32_e32 v31, v0
	v_mov_b32_e32 v40, v0
	v_mov_b32_e32 v41, v0
	v_mov_b32_e32 v42, v0
	v_mov_b32_e32 v43, v0
	v_mov_b32_e32 v44, v0
	v_mov_b32_e32 v45, v0
	v_mov_b32_e32 v46, v0
	v_mov_b32_e32 v47, v0
	v_mov_b32_e32 v16, v0
	v_mov_b32_e32 v17, v0
	v_mov_b32_e32 v18, v0
	v_mov_b32_e32 v19, v0
	v_mov_b32_e32 v20, v0
	v_mov_b32_e32 v21, v0
	v_mov_b32_e32 v22, v0
	v_mov_b32_e32 v23, v0
	v_mov_b32_e32 v32, v0
	v_mov_b32_e32 v33, v0
	v_mov_b32_e32 v34, v0
	v_mov_b32_e32 v35, v0
	v_mov_b32_e32 v36, v0
	v_mov_b32_e32 v37, v0
	v_mov_b32_e32 v38, v0
	v_mov_b32_e32 v39, v0
	v_mov_b32_e32 v48, v0
	v_mov_b32_e32 v49, v0
	v_mov_b32_e32 v50, v0
	v_mov_b32_e32 v51, v0
	v_mov_b32_e32 v52, v0
	v_mov_b32_e32 v53, v0
	v_mov_b32_e32 v54, v0
	v_mov_b32_e32 v55, v0
	v_mov_b32_e32 v56, v0
	v_mov_b32_e32 v57, v0
	v_mov_b32_e32 v58, v0
	v_mov_b32_e32 v59, v0
	v_mov_b32_e32 v60, v0
	v_mov_b32_e32 v61, v0
	v_mov_b32_e32 v62, v0
	v_mov_b32_e32 v63, v0
	v_mov_b32_e32 v64, v0
	v_mov_b32_e32 v65, v0
	v_mov_b32_e32 v66, v0
	v_mov_b32_e32 v67, v0
	v_mov_b32_e32 v68, v0
	v_mov_b32_e32 v69, v0
	v_mov_b32_e32 v70, v0
	v_mov_b32_e32 v71, v0
	v_mov_b32_e32 v72, v0
	v_mov_b32_e32 v73, v0
	v_mov_b32_e32 v74, v0
	v_mov_b32_e32 v75, v0
	v_mov_b32_e32 v76, v0
	v_mov_b32_e32 v77, v0
	v_mov_b32_e32 v78, v0
	v_mov_b32_e32 v79, v0
	v_mov_b32_e32 v88, v0
	v_mov_b32_e32 v89, v0
	v_mov_b32_e32 v90, v0
	v_mov_b32_e32 v91, v0
	v_mov_b32_e32 v92, v0
	v_mov_b32_e32 v93, v0
	v_mov_b32_e32 v94, v0
	v_mov_b32_e32 v95, v0
	v_mov_b32_e32 v104, v0
	v_mov_b32_e32 v105, v0
	v_mov_b32_e32 v106, v0
	v_mov_b32_e32 v107, v0
	v_mov_b32_e32 v108, v0
	v_mov_b32_e32 v109, v0
	v_mov_b32_e32 v110, v0
	v_mov_b32_e32 v111, v0
	v_mov_b32_e32 v80, v0
	v_mov_b32_e32 v81, v0
	v_mov_b32_e32 v82, v0
	v_mov_b32_e32 v83, v0
	v_mov_b32_e32 v84, v0
	v_mov_b32_e32 v85, v0
	v_mov_b32_e32 v86, v0
	v_mov_b32_e32 v87, v0
	v_mov_b32_e32 v96, v0
	v_mov_b32_e32 v97, v0
	v_mov_b32_e32 v98, v0
	v_mov_b32_e32 v99, v0
	v_mov_b32_e32 v100, v0
	v_mov_b32_e32 v101, v0
	v_mov_b32_e32 v102, v0
	v_mov_b32_e32 v103, v0
	v_mov_b32_e32 v112, v0
	v_mov_b32_e32 v113, v0
	v_mov_b32_e32 v114, v0
	v_mov_b32_e32 v115, v0
	v_mov_b32_e32 v116, v0
	v_mov_b32_e32 v117, v0
	v_mov_b32_e32 v118, v0
	v_mov_b32_e32 v119, v0
	v_mov_b32_e32 v120, v0
	v_mov_b32_e32 v121, v0
	v_mov_b32_e32 v122, v0
	v_mov_b32_e32 v123, v0
	v_mov_b32_e32 v124, v0
	v_mov_b32_e32 v125, v0
	v_mov_b32_e32 v126, v0
	v_mov_b32_e32 v127, v0
.LBB0_1073:
	s_add_u32 s18, s16, 0xfffc0080
	s_addc_u32 s19, s17, -1
	s_add_i32 s48, 0, 0x10000
	s_cmp_eq_u32 s47, 12
	s_cselect_b32 s21, s13, s19
	s_cselect_b32 s20, s12, s18
	s_cselect_b32 s19, s15, s46
	s_cselect_b32 s18, s14, s45
	s_add_i32 s50, 0, 0x14000
	v_add_u32_e32 v152, s48, v138
	v_add_u32_e32 v168, s50, v138
	ds_read_b128 v[140:143], v152
	ds_read_b128 v[144:147], v152 offset:1024
	ds_read_b128 v[148:151], v152 offset:2048
	ds_read_b128 v[152:155], v152 offset:3072
	ds_read_b128 v[156:159], v168
	ds_read_b128 v[160:163], v168 offset:1024
	ds_read_b128 v[164:167], v168 offset:2048
	ds_read_b128 v[168:171], v168 offset:3072
	v_lshl_add_u64 v[198:199], s[16:17], 0, v[136:137]
	s_add_i32 m0, s30, 0xc000
	ds_read_b128 v[172:175], v139
	ds_read_b128 v[176:179], v139 offset:1024
	ds_read_b128 v[180:183], v139 offset:2048
	ds_read_b128 v[184:187], v139 offset:3072
	ds_read_b128 v[188:191], v139 offset:4096
	ds_read_b128 v[192:195], v139 offset:5120
	ds_read_b128 v[206:209], v139 offset:6144
	ds_read_b128 v[210:213], v139 offset:7168
	global_load_lds_dwordx4 v[198:199], off
	v_lshl_add_u64 v[198:199], s[16:17], 0, v[134:135]
	s_add_i32 m0, s30, 0xe000
	s_nop 0
	global_load_lds_dwordx4 v[198:199], off
	s_waitcnt vmcnt(8)
	s_waitcnt lgkmcnt(0)
	s_barrier
	s_waitcnt lgkmcnt(0)
	v_mfma_f32_16x16x32_bf16 v[124:127], v[140:143], v[172:175], v[124:127]
	v_mfma_f32_16x16x32_bf16 v[120:123], v[148:151], v[172:175], v[120:123]
	v_mfma_f32_16x16x32_bf16 v[116:119], v[140:143], v[180:183], v[116:119]
	v_mfma_f32_16x16x32_bf16 v[112:115], v[148:151], v[180:183], v[112:115]
	v_mfma_f32_16x16x32_bf16 v[100:103], v[140:143], v[188:191], v[100:103]
	v_mfma_f32_16x16x32_bf16 v[96:99], v[148:151], v[188:191], v[96:99]
	v_mfma_f32_16x16x32_bf16 v[84:87], v[140:143], v[206:209], v[84:87]
	v_mfma_f32_16x16x32_bf16 v[80:83], v[148:151], v[206:209], v[80:83]
	v_mfma_f32_16x16x32_bf16 v[124:127], v[144:147], v[176:179], v[124:127]
	v_mfma_f32_16x16x32_bf16 v[120:123], v[152:155], v[176:179], v[120:123]
	v_mfma_f32_16x16x32_bf16 v[116:119], v[144:147], v[184:187], v[116:119]
	v_mfma_f32_16x16x32_bf16 v[112:115], v[152:155], v[184:187], v[112:115]
	v_mfma_f32_16x16x32_bf16 v[100:103], v[144:147], v[192:195], v[100:103]
	v_mfma_f32_16x16x32_bf16 v[96:99], v[152:155], v[192:195], v[96:99]
	v_mfma_f32_16x16x32_bf16 v[84:87], v[144:147], v[210:213], v[84:87]
	v_mfma_f32_16x16x32_bf16 v[80:83], v[152:155], v[210:213], v[80:83]
	v_mfma_f32_16x16x32_bf16 v[108:111], v[156:159], v[172:175], v[108:111]
	v_mfma_f32_16x16x32_bf16 v[104:107], v[164:167], v[172:175], v[104:107]
	v_mfma_f32_16x16x32_bf16 v[92:95], v[156:159], v[180:183], v[92:95]
	v_mfma_f32_16x16x32_bf16 v[88:91], v[164:167], v[180:183], v[88:91]
	v_mfma_f32_16x16x32_bf16 v[76:79], v[156:159], v[188:191], v[76:79]
	v_mfma_f32_16x16x32_bf16 v[72:75], v[164:167], v[188:191], v[72:75]
	v_mfma_f32_16x16x32_bf16 v[68:71], v[156:159], v[206:209], v[68:71]
	v_mfma_f32_16x16x32_bf16 v[64:67], v[164:167], v[206:209], v[64:67]
	v_mfma_f32_16x16x32_bf16 v[108:111], v[160:163], v[176:179], v[108:111]
	v_mfma_f32_16x16x32_bf16 v[104:107], v[168:171], v[176:179], v[104:107]
	v_mfma_f32_16x16x32_bf16 v[92:95], v[160:163], v[184:187], v[92:95]
	v_mfma_f32_16x16x32_bf16 v[88:91], v[168:171], v[184:187], v[88:91]
	v_mfma_f32_16x16x32_bf16 v[76:79], v[160:163], v[192:195], v[76:79]
	v_mfma_f32_16x16x32_bf16 v[72:75], v[168:171], v[192:195], v[72:75]
	v_mfma_f32_16x16x32_bf16 v[68:71], v[160:163], v[210:213], v[68:71]
	v_mfma_f32_16x16x32_bf16 v[64:67], v[168:171], v[210:213], v[64:67]
	s_barrier
; #define PG8_STAGE(bufoff, gbase, voff) do { _Pragma("unroll") for (int _i = 0; _i < 2; ++_i) \
;         __builtin_amdgcn_global_load_lds((const unsigned*)((const char*)(gbase) + (voff)[_i]), (LAS unsigned*)(lds + (bufoff) + ldsw + _i * 8192), 16, 0, 0); } while (0)
; #define PG8_LDA(dst, b, h) do { _Pragma("unroll") for (int m = 0; m < 4; ++m) _Pragma("unroll") for (int k = 0; k < 2; ++k) dst[m][k] = *(const LAS bf16x8*)(lds + PG8_SA(b, h) + aoff + m * 2048 + k * 1024); } while (0)
; #define PG8_LDB(dst, b, h) do { _Pragma("unroll") for (int n = 0; n < 2; ++n) _Pragma("unroll") for (int k = 0; k < 2; ++k) dst[n][k] = *(const LAS bf16x8*)(lds + PG8_SB(b, h) + boff + n * 2048 + k * 1024); } while (0)
; #define PG8_MMA(ai, bj, At, Bt) do { __builtin_amdgcn_s_setprio(1); _Pragma("unroll") for (int m = 0; m < 4; ++m) _Pragma("unroll") for (int n = 0; n < 2; ++n) _Pragma("unroll") for (int k = 0; k < 2; ++k) \
;         acc[ai][bj][m][n] = __builtin_amdgcn_mfma_f32_16x16x32_bf16(Bt[n][k], At[m][k], acc[ai][bj][m][n], 0, 0, 0); __builtin_amdgcn_s_setprio(0); } while (0)
; #define PG8_WAIT_V(n) asm volatile("s_waitcnt vmcnt(" #n ")" ::: "memory")
; #define PG8_WAIT_L(n) asm volatile("s_waitcnt lgkmcnt(" #n ")" ::: "memory")
; #define PG8_BAR __builtin_amdgcn_s_barrier()
; #define PG8_SCHED __builtin_amdgcn_sched_barrier(0)
; template <class Epi, class Sched>
; __device__ __forceinline__ void gemm_phase(LAS unsigned char* lds, const GemmP g, const Sched& S, const Epi& E, int tid) {
;     ...
;             PG8_LDA(At, 0, 1); PG8_STAGE(PG8_SB(0, 0), b2, voffB); PG8_STAGE(PG8_SB(0, 1), b2 + hstepB, voffB); PG8_STAGE(PG8_SA(0, 0), a2, voffA);
;             PG8_WAIT_V(8); PG8_WAIT_L(0); PG8_BAR; PG8_MMA(1, 0, At, B0); PG8_MMA(1, 1, At, B1); PG8_BAR; PG8_SCHED;
;             PG8_LDB(B0, 1, 0); PG8_LDB(B1, 1, 1); PG8_SCHED; PG8_LDA(At, 1, 0); PG8_STAGE(PG8_SA(0, 1), a2 + hstepA, voffA);
;             PG8_WAIT_V(8); PG8_WAIT_L(0); PG8_BAR; PG8_MMA(0, 0, At, B0); PG8_MMA(0, 1, At, B1); PG8_BAR; PG8_SCHED;
	s_add_i32 s48, s48, s25
	v_lshl_add_u64 v[198:199], s[18:19], 0, v[196:197]
	s_mov_b32 m0, s48
	ds_read_b128 v[172:175], v139 offset:16384
	ds_read_b128 v[176:179], v139 offset:17408
	ds_read_b128 v[180:183], v139 offset:18432
	ds_read_b128 v[184:187], v139 offset:19456
	ds_read_b128 v[188:191], v139 offset:20480
	ds_read_b128 v[192:195], v139 offset:21504
	ds_read_b128 v[206:209], v139 offset:22528
	ds_read_b128 v[210:213], v139 offset:23552
	global_load_lds_dwordx4 v[198:199], off
	s_add_i32 m0, s48, 0x2000
	s_add_u32 s48, s18, 0x40000
	v_lshl_add_u64 v[200:201], s[18:19], 0, v[128:129]
	s_addc_u32 s49, s19, 0
	s_add_i32 s50, s50, s25
	global_load_lds_dwordx4 v[200:201], off
	v_lshl_add_u64 v[214:215], s[48:49], 0, v[196:197]
	s_mov_b32 m0, s50
	v_lshl_add_u64 v[216:217], s[20:21], 0, v[130:131]
	global_load_lds_dwordx4 v[214:215], off
	v_lshl_add_u64 v[214:215], s[48:49], 0, v[128:129]
	s_add_i32 m0, s50, 0x2000
	s_nop 0
	global_load_lds_dwordx4 v[214:215], off
	v_lshl_add_u64 v[214:215], s[20:21], 0, v[132:133]
	s_mov_b32 m0, s30
	s_nop 0
	global_load_lds_dwordx4 v[214:215], off
	s_mov_b32 m0, s31
	s_nop 0
	global_load_lds_dwordx4 v[216:217], off
	s_waitcnt vmcnt(8)
	s_waitcnt lgkmcnt(0)
	s_barrier
	s_waitcnt lgkmcnt(0)
	v_mfma_f32_16x16x32_bf16 v[60:63], v[140:143], v[172:175], v[60:63]
	v_mfma_f32_16x16x32_bf16 v[56:59], v[148:151], v[172:175], v[56:59]
	v_mfma_f32_16x16x32_bf16 v[52:55], v[140:143], v[180:183], v[52:55]
	v_mfma_f32_16x16x32_bf16 v[48:51], v[148:151], v[180:183], v[48:51]
	v_mfma_f32_16x16x32_bf16 v[36:39], v[140:143], v[188:191], v[36:39]
	v_mfma_f32_16x16x32_bf16 v[32:35], v[148:151], v[188:191], v[32:35]
	v_mfma_f32_16x16x32_bf16 v[20:23], v[140:143], v[206:209], v[20:23]
	v_mfma_f32_16x16x32_bf16 v[16:19], v[148:151], v[206:209], v[16:19]
	v_mfma_f32_16x16x32_bf16 v[60:63], v[144:147], v[176:179], v[60:63]
	v_mfma_f32_16x16x32_bf16 v[56:59], v[152:155], v[176:179], v[56:59]
	v_mfma_f32_16x16x32_bf16 v[52:55], v[144:147], v[184:187], v[52:55]
	v_mfma_f32_16x16x32_bf16 v[48:51], v[152:155], v[184:187], v[48:51]
	v_mfma_f32_16x16x32_bf16 v[36:39], v[144:147], v[192:195], v[36:39]
	v_mfma_f32_16x16x32_bf16 v[32:35], v[152:155], v[192:195], v[32:35]
	v_mfma_f32_16x16x32_bf16 v[20:23], v[144:147], v[210:213], v[20:23]
	v_mfma_f32_16x16x32_bf16 v[16:19], v[152:155], v[210:213], v[16:19]
	v_mfma_f32_16x16x32_bf16 v[44:47], v[156:159], v[172:175], v[44:47]
	v_mfma_f32_16x16x32_bf16 v[40:43], v[164:167], v[172:175], v[40:43]
	v_mfma_f32_16x16x32_bf16 v[28:31], v[156:159], v[180:183], v[28:31]
	v_mfma_f32_16x16x32_bf16 v[24:27], v[164:167], v[180:183], v[24:27]
	v_mfma_f32_16x16x32_bf16 v[12:15], v[156:159], v[188:191], v[12:15]
	v_mfma_f32_16x16x32_bf16 v[8:11], v[164:167], v[188:191], v[8:11]
	v_mfma_f32_16x16x32_bf16 v[4:7], v[156:159], v[206:209], v[4:7]
	v_mfma_f32_16x16x32_bf16 v[0:3], v[164:167], v[206:209], v[0:3]
	v_mfma_f32_16x16x32_bf16 v[44:47], v[160:163], v[176:179], v[44:47]
	v_mfma_f32_16x16x32_bf16 v[40:43], v[168:171], v[176:179], v[40:43]
	v_mfma_f32_16x16x32_bf16 v[28:31], v[160:163], v[184:187], v[28:31]
	v_mfma_f32_16x16x32_bf16 v[24:27], v[168:171], v[184:187], v[24:27]
	v_mfma_f32_16x16x32_bf16 v[12:15], v[160:163], v[192:195], v[12:15]
	v_mfma_f32_16x16x32_bf16 v[8:11], v[168:171], v[192:195], v[8:11]
	v_mfma_f32_16x16x32_bf16 v[4:7], v[160:163], v[210:213], v[4:7]
	v_mfma_f32_16x16x32_bf16 v[0:3], v[168:171], v[210:213], v[0:3]
	s_barrier
	s_add_i32 s48, 0, 0x18000
	s_add_i32 s49, 0, 0x1c000
	v_add_u32_e32 v152, s48, v138
	v_add_u32_e32 v168, s49, v138
	ds_read_b128 v[140:143], v152
	ds_read_b128 v[144:147], v152 offset:1024
	ds_read_b128 v[148:151], v152 offset:2048
	ds_read_b128 v[152:155], v152 offset:3072
	ds_read_b128 v[156:159], v168
	ds_read_b128 v[160:163], v168 offset:1024
	ds_read_b128 v[164:167], v168 offset:2048
	ds_read_b128 v[168:171], v168 offset:3072
	s_add_u32 s20, s20, 0x40000
	s_addc_u32 s21, s21, 0
	s_mov_b32 m0, s34
	v_lshl_add_u64 v[220:221], s[20:21], 0, v[132:133]
	ds_read_b128 v[172:175], v139 offset:32768
	ds_read_b128 v[176:179], v139 offset:33792
	ds_read_b128 v[180:183], v139 offset:34816
	ds_read_b128 v[184:187], v139 offset:35840
	ds_read_b128 v[188:191], v139 offset:36864
	ds_read_b128 v[192:195], v139 offset:37888
	ds_read_b128 v[206:209], v139 offset:38912
	ds_read_b128 v[210:213], v139 offset:39936
	global_load_lds_dwordx4 v[220:221], off
	v_lshl_add_u64 v[220:221], s[20:21], 0, v[130:131]
	s_mov_b32 m0, s35
	s_nop 0
	global_load_lds_dwordx4 v[220:221], off
	s_waitcnt vmcnt(8)
	s_waitcnt lgkmcnt(0)
	s_barrier
; #define PG8_STAGE(bufoff, gbase, voff) do { _Pragma("unroll") for (int _i = 0; _i < 2; ++_i) \
;         __builtin_amdgcn_global_load_lds((const unsigned*)((const char*)(gbase) + (voff)[_i]), (LAS unsigned*)(lds + (bufoff) + ldsw + _i * 8192), 16, 0, 0); } while (0)
; #define PG8_LDA(dst, b, h) do { _Pragma("unroll") for (int m = 0; m < 4; ++m) _Pragma("unroll") for (int k = 0; k < 2; ++k) dst[m][k] = *(const LAS bf16x8*)(lds + PG8_SA(b, h) + aoff + m * 2048 + k * 1024); } while (0)
; #define PG8_MMA(ai, bj, At, Bt) do { __builtin_amdgcn_s_setprio(1); _Pragma("unroll") for (int m = 0; m < 4; ++m) _Pragma("unroll") for (int n = 0; n < 2; ++n) _Pragma("unroll") for (int k = 0; k < 2; ++k) \
;         acc[ai][bj][m][n] = __builtin_amdgcn_mfma_f32_16x16x32_bf16(Bt[n][k], At[m][k], acc[ai][bj][m][n], 0, 0, 0); __builtin_amdgcn_s_setprio(0); } while (0)
; #define PG8_WAIT_V(n) asm volatile("s_waitcnt vmcnt(" #n ")" ::: "memory")
; #define PG8_WAIT_L(n) asm volatile("s_waitcnt lgkmcnt(" #n ")" ::: "memory")
; #define PG8_BAR __builtin_amdgcn_s_barrier()
; #define PG8_SCHED __builtin_amdgcn_sched_barrier(0)
; template <class Epi, class Sched>
; __device__ __forceinline__ void gemm_phase(LAS unsigned char* lds, const GemmP g, const Sched& S, const Epi& E, int tid) {
;     ...
;             PG8_WAIT_V(8); PG8_WAIT_L(0); PG8_BAR; PG8_MMA(0, 0, At, B0); PG8_MMA(0, 1, At, B1); PG8_BAR; PG8_SCHED;
;             PG8_LDA(At, 1, 1); PG8_STAGE(PG8_SB(1, 0), b3, voffB); PG8_STAGE(PG8_SB(1, 1), b3 + hstepB, voffB); PG8_STAGE(PG8_SA(1, 0), a3, voffA);
;             PG8_WAIT_V(8); PG8_WAIT_L(0); PG8_BAR; PG8_MMA(1, 0, At, B0); PG8_MMA(1, 1, At, B1); PG8_BAR; PG8_SCHED;
;         }
;         if (wr == 0) PG8_BAR;
	s_waitcnt lgkmcnt(0)
	v_mfma_f32_16x16x32_bf16 v[124:127], v[140:143], v[172:175], v[124:127]
	v_mfma_f32_16x16x32_bf16 v[120:123], v[148:151], v[172:175], v[120:123]
	v_mfma_f32_16x16x32_bf16 v[116:119], v[140:143], v[180:183], v[116:119]
	v_mfma_f32_16x16x32_bf16 v[112:115], v[148:151], v[180:183], v[112:115]
	v_mfma_f32_16x16x32_bf16 v[100:103], v[140:143], v[188:191], v[100:103]
	v_mfma_f32_16x16x32_bf16 v[96:99], v[148:151], v[188:191], v[96:99]
	v_mfma_f32_16x16x32_bf16 v[84:87], v[140:143], v[206:209], v[84:87]
	v_mfma_f32_16x16x32_bf16 v[80:83], v[148:151], v[206:209], v[80:83]
	v_mfma_f32_16x16x32_bf16 v[124:127], v[144:147], v[176:179], v[124:127]
	v_mfma_f32_16x16x32_bf16 v[120:123], v[152:155], v[176:179], v[120:123]
	v_mfma_f32_16x16x32_bf16 v[116:119], v[144:147], v[184:187], v[116:119]
	v_mfma_f32_16x16x32_bf16 v[112:115], v[152:155], v[184:187], v[112:115]
	v_mfma_f32_16x16x32_bf16 v[100:103], v[144:147], v[192:195], v[100:103]
	v_mfma_f32_16x16x32_bf16 v[96:99], v[152:155], v[192:195], v[96:99]
	v_mfma_f32_16x16x32_bf16 v[84:87], v[144:147], v[210:213], v[84:87]
	v_mfma_f32_16x16x32_bf16 v[80:83], v[152:155], v[210:213], v[80:83]
	v_mfma_f32_16x16x32_bf16 v[108:111], v[156:159], v[172:175], v[108:111]
	v_mfma_f32_16x16x32_bf16 v[104:107], v[164:167], v[172:175], v[104:107]
	v_mfma_f32_16x16x32_bf16 v[92:95], v[156:159], v[180:183], v[92:95]
	v_mfma_f32_16x16x32_bf16 v[88:91], v[164:167], v[180:183], v[88:91]
	v_mfma_f32_16x16x32_bf16 v[76:79], v[156:159], v[188:191], v[76:79]
	v_mfma_f32_16x16x32_bf16 v[72:75], v[164:167], v[188:191], v[72:75]
	v_mfma_f32_16x16x32_bf16 v[68:71], v[156:159], v[206:209], v[68:71]
	v_mfma_f32_16x16x32_bf16 v[64:67], v[164:167], v[206:209], v[64:67]
	v_mfma_f32_16x16x32_bf16 v[108:111], v[160:163], v[176:179], v[108:111]
	v_mfma_f32_16x16x32_bf16 v[104:107], v[168:171], v[176:179], v[104:107]
	v_mfma_f32_16x16x32_bf16 v[92:95], v[160:163], v[184:187], v[92:95]
	v_mfma_f32_16x16x32_bf16 v[88:91], v[168:171], v[184:187], v[88:91]
	v_mfma_f32_16x16x32_bf16 v[76:79], v[160:163], v[192:195], v[76:79]
	v_mfma_f32_16x16x32_bf16 v[72:75], v[168:171], v[192:195], v[72:75]
	v_mfma_f32_16x16x32_bf16 v[68:71], v[160:163], v[210:213], v[68:71]
	v_mfma_f32_16x16x32_bf16 v[64:67], v[168:171], v[210:213], v[64:67]
	s_barrier
	s_add_i32 s20, s48, s25
	v_lshl_add_u64 v[198:199], v[198:199], 0, s[80:81]
	s_mov_b32 m0, s20
	ds_read_b128 v[172:175], v139 offset:49152
	ds_read_b128 v[176:179], v139 offset:50176
	ds_read_b128 v[180:183], v139 offset:51200
	ds_read_b128 v[184:187], v139 offset:52224
	ds_read_b128 v[188:191], v139 offset:53248
	ds_read_b128 v[192:195], v139 offset:54272
	ds_read_b128 v[206:209], v139 offset:55296
	ds_read_b128 v[210:213], v139 offset:56320
	global_load_lds_dwordx4 v[198:199], off
	s_add_i32 m0, s20, 0x2000
	s_add_u32 s18, s18, 0x40080
	v_lshl_add_u64 v[198:199], v[200:201], 0, s[80:81]
	s_addc_u32 s19, s19, 0
	s_add_i32 s20, s49, s25
	global_load_lds_dwordx4 v[198:199], off
	v_lshl_add_u64 v[198:199], s[18:19], 0, v[196:197]
	s_mov_b32 m0, s20
	s_nop 0
	global_load_lds_dwordx4 v[198:199], off
	v_lshl_add_u64 v[198:199], s[18:19], 0, v[128:129]
	s_add_i32 m0, s20, 0x2000
	s_nop 0
	global_load_lds_dwordx4 v[198:199], off
	v_lshl_add_u64 v[198:199], v[214:215], 0, s[80:81]
	s_mov_b32 m0, s38
	s_nop 0
	global_load_lds_dwordx4 v[198:199], off
	v_lshl_add_u64 v[198:199], v[216:217], 0, s[80:81]
	s_mov_b32 m0, s39
	s_nop 0
	global_load_lds_dwordx4 v[198:199], off
	s_waitcnt vmcnt(8)
	s_waitcnt lgkmcnt(0)
	s_barrier
	s_waitcnt lgkmcnt(0)
	v_mfma_f32_16x16x32_bf16 v[60:63], v[140:143], v[172:175], v[60:63]
	v_mfma_f32_16x16x32_bf16 v[56:59], v[148:151], v[172:175], v[56:59]
	v_mfma_f32_16x16x32_bf16 v[52:55], v[140:143], v[180:183], v[52:55]
	v_mfma_f32_16x16x32_bf16 v[48:51], v[148:151], v[180:183], v[48:51]
	v_mfma_f32_16x16x32_bf16 v[36:39], v[140:143], v[188:191], v[36:39]
	v_mfma_f32_16x16x32_bf16 v[32:35], v[148:151], v[188:191], v[32:35]
	v_mfma_f32_16x16x32_bf16 v[20:23], v[140:143], v[206:209], v[20:23]
	v_mfma_f32_16x16x32_bf16 v[16:19], v[148:151], v[206:209], v[16:19]
	v_mfma_f32_16x16x32_bf16 v[60:63], v[144:147], v[176:179], v[60:63]
	v_mfma_f32_16x16x32_bf16 v[56:59], v[152:155], v[176:179], v[56:59]
	v_mfma_f32_16x16x32_bf16 v[52:55], v[144:147], v[184:187], v[52:55]
	v_mfma_f32_16x16x32_bf16 v[48:51], v[152:155], v[184:187], v[48:51]
	v_mfma_f32_16x16x32_bf16 v[36:39], v[144:147], v[192:195], v[36:39]
	v_mfma_f32_16x16x32_bf16 v[32:35], v[152:155], v[192:195], v[32:35]
	v_mfma_f32_16x16x32_bf16 v[20:23], v[144:147], v[210:213], v[20:23]
	v_mfma_f32_16x16x32_bf16 v[16:19], v[152:155], v[210:213], v[16:19]
	v_mfma_f32_16x16x32_bf16 v[44:47], v[156:159], v[172:175], v[44:47]
	v_mfma_f32_16x16x32_bf16 v[40:43], v[164:167], v[172:175], v[40:43]
	v_mfma_f32_16x16x32_bf16 v[28:31], v[156:159], v[180:183], v[28:31]
	v_mfma_f32_16x16x32_bf16 v[24:27], v[164:167], v[180:183], v[24:27]
	v_mfma_f32_16x16x32_bf16 v[12:15], v[156:159], v[188:191], v[12:15]
	v_mfma_f32_16x16x32_bf16 v[8:11], v[164:167], v[188:191], v[8:11]
	v_mfma_f32_16x16x32_bf16 v[4:7], v[156:159], v[206:209], v[4:7]
	v_mfma_f32_16x16x32_bf16 v[0:3], v[164:167], v[206:209], v[0:3]
	v_mfma_f32_16x16x32_bf16 v[44:47], v[160:163], v[176:179], v[44:47]
	v_mfma_f32_16x16x32_bf16 v[40:43], v[168:171], v[176:179], v[40:43]
	v_mfma_f32_16x16x32_bf16 v[28:31], v[160:163], v[184:187], v[28:31]
	v_mfma_f32_16x16x32_bf16 v[24:27], v[168:171], v[184:187], v[24:27]
	v_mfma_f32_16x16x32_bf16 v[12:15], v[160:163], v[192:195], v[12:15]
	v_mfma_f32_16x16x32_bf16 v[8:11], v[168:171], v[192:195], v[8:11]
	v_mfma_f32_16x16x32_bf16 v[4:7], v[160:163], v[210:213], v[4:7]
	v_mfma_f32_16x16x32_bf16 v[0:3], v[168:171], v[210:213], v[0:3]
	s_barrier
	s_add_i32 s47, s47, 2
	s_add_u32 s45, s45, 0x100
	s_addc_u32 s46, s46, 0
	s_add_u32 s16, s16, 0x100
	s_addc_u32 s17, s17, 0
	s_cmp_gt_u32 s47, 13
	s_cbranch_scc0 .LBB0_1073
	s_setprio 0
	s_and_b64 vcc, exec, s[8:9]
	s_cbranch_vccz .LBB0_1076
	s_barrier

; #define PG8_STAGE(bufoff, gbase, voff) do { _Pragma("unroll") for (int _i = 0; _i < 2; ++_i) \
;         __builtin_amdgcn_global_load_lds((const unsigned*)((const char*)(gbase) + (voff)[_i]), (LAS unsigned*)(lds + (bufoff) + ldsw + _i * 8192), 16, 0, 0); } while (0)
; #define PG8_LDA(dst, b, h) do { _Pragma("unroll") for (int m = 0; m < 4; ++m) _Pragma("unroll") for (int k = 0; k < 2; ++k) dst[m][k] = *(const LAS bf16x8*)(lds + PG8_SA(b, h) + aoff + m * 2048 + k * 1024); } while (0)
; #define PG8_LDB(dst, b, h) do { _Pragma("unroll") for (int n = 0; n < 2; ++n) _Pragma("unroll") for (int k = 0; k < 2; ++k) dst[n][k] = *(const LAS bf16x8*)(lds + PG8_SB(b, h) + boff + n * 2048 + k * 1024); } while (0)
; #define PG8_SCHED __builtin_amdgcn_sched_barrier(0)
; template <class Epi, class Sched>
; __device__ __forceinline__ void gemm_phase(LAS unsigned char* lds, const GemmP g, const Sched& S, const Epi& E, int tid) {
;     ...
;         for (int t = 0; t < nt; t += 2) {
;             const bool last = (t == nt - 2);
;             const char* a1 = cA + (size_t)(t + 1) * kstep;
;             const char* a2 = last ? nA : cA + (size_t)(t + 2) * kstep; const char* b2 = last ? nB : cB + (size_t)(t + 2) * kstep;
;             const char* a3 = a2 + kstep; const char* b3 = b2 + kstep;
;             PG8_LDB(B0, 0, 0); PG8_LDB(B1, 0, 1); PG8_SCHED; PG8_LDA(At, 0, 0); PG8_STAGE(PG8_SA(1, 1), a1 + hstepA, voffA);
;     ...
; #pragma unroll
;         for (int a = 0; a < 2; ++a)
; #pragma unroll
;             for (int b = 0; b < 2; ++b)
; #pragma unroll
;                 for (int m = 0; m < 4; ++m)
; #pragma unroll
;                     for (int n = 0; n < 2; ++n) acc[a][b][m][n] = (f32x4){0.f, 0.f, 0.f, 0.f};
;         cur = nxt; cA = nA; cB = nB; ++ui;
.LBB0_1162:
	s_add_u32 s12, s8, 0x100
	s_addc_u32 s13, s9, 0
	s_add_u32 s6, s6, 0x40080
	v_mov_b32_e32 v0, 0
	s_addc_u32 s7, s7, 0
	s_mov_b32 s14, -2
	s_waitcnt lgkmcnt(0)
	v_mov_b32_e32 v1, v0
	v_mov_b32_e32 v2, v0
	v_mov_b32_e32 v3, v0
	v_mov_b32_e32 v4, v0
	v_mov_b32_e32 v5, v0
	v_mov_b32_e32 v6, v0
	v_mov_b32_e32 v7, v0
	v_mov_b32_e32 v8, v0
	v_mov_b32_e32 v9, v0
	v_mov_b32_e32 v10, v0
	v_mov_b32_e32 v11, v0
	v_mov_b32_e32 v12, v0
	v_mov_b32_e32 v13, v0
	v_mov_b32_e32 v14, v0
	v_mov_b32_e32 v15, v0
	v_mov_b32_e32 v16, v0
	v_mov_b32_e32 v17, v0
	v_mov_b32_e32 v18, v0
	v_mov_b32_e32 v19, v0
	v_mov_b32_e32 v20, v0
	v_mov_b32_e32 v21, v0
	v_mov_b32_e32 v22, v0
	v_mov_b32_e32 v23, v0
	v_mov_b32_e32 v24, v0
	v_mov_b32_e32 v25, v0
	v_mov_b32_e32 v26, v0
	v_mov_b32_e32 v27, v0
	v_mov_b32_e32 v28, v0
	v_mov_b32_e32 v29, v0
	v_mov_b32_e32 v30, v0
	v_mov_b32_e32 v31, v0
	v_mov_b32_e32 v56, v0
	v_mov_b32_e32 v57, v0
	v_mov_b32_e32 v58, v0
	v_mov_b32_e32 v59, v0
	v_mov_b32_e32 v64, v0
	v_mov_b32_e32 v65, v0
	v_mov_b32_e32 v66, v0
	v_mov_b32_e32 v67, v0
	v_mov_b32_e32 v72, v0
	v_mov_b32_e32 v73, v0
	v_mov_b32_e32 v74, v0
	v_mov_b32_e32 v75, v0
	v_mov_b32_e32 v76, v0
	v_mov_b32_e32 v77, v0
	v_mov_b32_e32 v78, v0
	v_mov_b32_e32 v79, v0
	v_mov_b32_e32 v80, v0
	v_mov_b32_e32 v81, v0
	v_mov_b32_e32 v82, v0
	v_mov_b32_e32 v83, v0
	v_mov_b32_e32 v84, v0
	v_mov_b32_e32 v85, v0
	v_mov_b32_e32 v86, v0
	v_mov_b32_e32 v87, v0
	v_mov_b32_e32 v88, v0
	v_mov_b32_e32 v89, v0
	v_mov_b32_e32 v90, v0
	v_mov_b32_e32 v91, v0
	v_mov_b32_e32 v92, v0
	v_mov_b32_e32 v93, v0
	v_mov_b32_e32 v94, v0
	v_mov_b32_e32 v95, v0
	v_mov_b32_e32 v32, v0
	v_mov_b32_e32 v33, v0
	v_mov_b32_e32 v34, v0
	v_mov_b32_e32 v35, v0
	v_mov_b32_e32 v36, v0
	v_mov_b32_e32 v37, v0
	v_mov_b32_e32 v38, v0
	v_mov_b32_e32 v39, v0
	v_mov_b32_e32 v40, v0
	v_mov_b32_e32 v41, v0
	v_mov_b32_e32 v42, v0
	v_mov_b32_e32 v43, v0
	v_mov_b32_e32 v44, v0
	v_mov_b32_e32 v45, v0
	v_mov_b32_e32 v46, v0
	v_mov_b32_e32 v47, v0
	v_mov_b32_e32 v48, v0
	v_mov_b32_e32 v49, v0
	v_mov_b32_e32 v50, v0
	v_mov_b32_e32 v51, v0
	v_mov_b32_e32 v52, v0
	v_mov_b32_e32 v53, v0
	v_mov_b32_e32 v54, v0
	v_mov_b32_e32 v55, v0
	v_mov_b32_e32 v60, v0
	v_mov_b32_e32 v61, v0
	v_mov_b32_e32 v62, v0
	v_mov_b32_e32 v63, v0
	v_mov_b32_e32 v68, v0
	v_mov_b32_e32 v69, v0
	v_mov_b32_e32 v70, v0
	v_mov_b32_e32 v71, v0
	v_mov_b32_e32 v96, v0
	v_mov_b32_e32 v97, v0
	v_mov_b32_e32 v98, v0
	v_mov_b32_e32 v99, v0
	v_mov_b32_e32 v100, v0
	v_mov_b32_e32 v101, v0
	v_mov_b32_e32 v102, v0
	v_mov_b32_e32 v103, v0
	v_mov_b32_e32 v104, v0
	v_mov_b32_e32 v105, v0
	v_mov_b32_e32 v106, v0
	v_mov_b32_e32 v107, v0
	v_mov_b32_e32 v108, v0
	v_mov_b32_e32 v109, v0
	v_mov_b32_e32 v110, v0
	v_mov_b32_e32 v111, v0
	v_mov_b32_e32 v112, v0
	v_mov_b32_e32 v113, v0
	v_mov_b32_e32 v114, v0
	v_mov_b32_e32 v115, v0
	v_mov_b32_e32 v116, v0
	v_mov_b32_e32 v117, v0
	v_mov_b32_e32 v118, v0
	v_mov_b32_e32 v119, v0
	v_mov_b32_e32 v128, v0
	v_mov_b32_e32 v129, v0
	v_mov_b32_e32 v130, v0
	v_mov_b32_e32 v131, v0
	v_mov_b32_e32 v120, v0
	v_mov_b32_e32 v121, v0
	v_mov_b32_e32 v122, v0
	v_mov_b32_e32 v123, v0
	s_sub_i32 s32, s41, s4
	s_bfe_u32 s98, s32, 0x10006
	s_bfe_u32 s32, s32, 0x10007
	s_cmp_lg_u64 s[2:3], 0
	s_cselect_b32 s99, 1, 0
	s_xor_b32 s98, s98, s99
	s_or_b32 s99, s98, s32
	s_xor_b32 s32, s32, 1
	s_or_b32 s98, s98, s32
	s_cmp_eq_u32 s40, 0x7fffffff
	s_cselect_b32 s32, 0, s99
	s_cselect_b32 s98, 0, s98
	s_and_b32 s99, s32, s98
.LBB0_1163:
	s_add_u32 s8, s6, 0xfffc0080
	s_addc_u32 s9, s7, -1
	s_add_i32 s15, 0, 0x10000
	s_cmp_eq_u32 s14, 12
	s_cselect_b32 s11, s93, s9
	s_cselect_b32 s10, s92, s8
	s_cselect_b32 s9, s95, s13
	s_cselect_b32 s8, s94, s12
	s_add_i32 s18, 0, 0x14000
	v_add_u32_e32 v140, s15, v214
	v_add_u32_e32 v156, s18, v214
	s_cmp_lg_u32 s99, 0
	s_cbranch_scc1 .Lskr_co_1
	ds_read_b128 v[124:127], v140
	ds_read_b128 v[132:135], v140 offset:1024
	ds_read_b128 v[136:139], v140 offset:2048
	ds_read_b128 v[140:143], v140 offset:3072
	ds_read_b128 v[144:147], v156
	ds_read_b128 v[148:151], v156 offset:1024
	ds_read_b128 v[152:155], v156 offset:2048
	ds_read_b128 v[156:159], v156 offset:3072
